# speedup vs baseline: 1.0274x; 1.0171x over previous
; __device__ __forceinline__ void prep_mod_job(const Params& p, int m, float* sm) {
;     ...
;   int col = tid & 63, kq = tid >> 6;
;   float acc[8];
; #pragma unroll
;   for (int s = 0; s < 8; ++s) acc[s] = 0.f;
;   const float* wp = p.ada_w + (size_t)l * 1024 * 9216 + (size_t)(kq * 256) * 9216 + col0 + col;
;   const float* scp = sc + kq * 256;
; #pragma unroll 8
;   for (int k = 0; k < 256; ++k) {
;     float w = wp[(size_t)k * 9216];
.LBB0_89:
	s_or_b64 exec, exec, s[4:5]
	s_mul_i32 s4, s11, 0x90
	s_sub_i32 s4, s40, s4
	s_sext_i32_i16 s4, s4
	s_lshl_b32 s4, s4, 6
	s_mul_i32 s6, s10, 0x2400000
	s_mul_hi_i32 s5, s10, 0x2400000
	s_add_u32 s6, s16, s6
	v_ashrrev_i32_e32 v37, 6, v35
	s_addc_u32 s7, s17, s5
	v_lshlrev_b32_e32 v4, 8, v37
	v_mov_b64_e32 v[2:3], s[6:7]
	v_and_b32_e32 v16, 63, v35
	v_mad_i64_i32 v[2:3], s[6:7], v4, s87, v[2:3]
	s_ashr_i32 s5, s4, 31
	v_lshl_add_u64 v[2:3], s[4:5], 2, v[2:3]
	v_lshlrev_b32_e32 v14, 2, v16
	v_mov_b32_e32 v20, 0
	v_lshl_add_u64 v[18:19], v[2:3], 0, v[14:15]
	v_lshl_add_u32 v14, v37, 10, s65
	s_mov_b64 s[6:7], 0
	v_mov_b32_e32 v21, v20
	v_mov_b32_e32 v22, v20
	v_mov_b32_e32 v23, v20
	v_mov_b32_e32 v24, v20
	v_mov_b32_e32 v25, v20
	v_mov_b32_e32 v26, v20
	v_mov_b32_e32 v27, v20
	s_waitcnt lgkmcnt(0)
	s_barrier
	v_mov_b64_e32 v[2:3], v[18:19]
	s_mov_b64 s[6:7], 0x9000
	v_mov_b32_e32 v4, v14
	global_load_dword v64, v[2:3], off
	v_lshl_add_u64 v[2:3], v[2:3], 0, s[6:7]
	global_load_dword v65, v[2:3], off
	v_lshl_add_u64 v[2:3], v[2:3], 0, s[6:7]
	global_load_dword v66, v[2:3], off
	v_lshl_add_u64 v[2:3], v[2:3], 0, s[6:7]
	global_load_dword v67, v[2:3], off
	v_lshl_add_u64 v[2:3], v[2:3], 0, s[6:7]
	global_load_dword v68, v[2:3], off
	v_lshl_add_u64 v[2:3], v[2:3], 0, s[6:7]
	global_load_dword v69, v[2:3], off
	v_lshl_add_u64 v[2:3], v[2:3], 0, s[6:7]
	global_load_dword v70, v[2:3], off
	v_lshl_add_u64 v[2:3], v[2:3], 0, s[6:7]
	global_load_dword v71, v[2:3], off
	v_lshl_add_u64 v[2:3], v[2:3], 0, s[6:7]
	global_load_dword v72, v[2:3], off
	v_lshl_add_u64 v[2:3], v[2:3], 0, s[6:7]
	global_load_dword v73, v[2:3], off
	v_lshl_add_u64 v[2:3], v[2:3], 0, s[6:7]
	global_load_dword v74, v[2:3], off
	v_lshl_add_u64 v[2:3], v[2:3], 0, s[6:7]
	global_load_dword v75, v[2:3], off
	v_lshl_add_u64 v[2:3], v[2:3], 0, s[6:7]
	global_load_dword v76, v[2:3], off
	v_lshl_add_u64 v[2:3], v[2:3], 0, s[6:7]
	global_load_dword v77, v[2:3], off
	v_lshl_add_u64 v[2:3], v[2:3], 0, s[6:7]
	global_load_dword v78, v[2:3], off
	v_lshl_add_u64 v[2:3], v[2:3], 0, s[6:7]
	global_load_dword v79, v[2:3], off
	v_lshl_add_u64 v[2:3], v[2:3], 0, s[6:7]
	global_load_dword v80, v[2:3], off
	v_lshl_add_u64 v[2:3], v[2:3], 0, s[6:7]
	global_load_dword v81, v[2:3], off
	v_lshl_add_u64 v[2:3], v[2:3], 0, s[6:7]
	global_load_dword v82, v[2:3], off
	v_lshl_add_u64 v[2:3], v[2:3], 0, s[6:7]
	global_load_dword v83, v[2:3], off
	v_lshl_add_u64 v[2:3], v[2:3], 0, s[6:7]
	global_load_dword v84, v[2:3], off
	v_lshl_add_u64 v[2:3], v[2:3], 0, s[6:7]
	global_load_dword v85, v[2:3], off
	v_lshl_add_u64 v[2:3], v[2:3], 0, s[6:7]
	global_load_dword v86, v[2:3], off
	v_lshl_add_u64 v[2:3], v[2:3], 0, s[6:7]
	global_load_dword v87, v[2:3], off
	v_lshl_add_u64 v[2:3], v[2:3], 0, s[6:7]
	global_load_dword v88, v[2:3], off
	v_lshl_add_u64 v[2:3], v[2:3], 0, s[6:7]
	global_load_dword v89, v[2:3], off
	v_lshl_add_u64 v[2:3], v[2:3], 0, s[6:7]
	global_load_dword v90, v[2:3], off
	v_lshl_add_u64 v[2:3], v[2:3], 0, s[6:7]
	global_load_dword v91, v[2:3], off
	v_lshl_add_u64 v[2:3], v[2:3], 0, s[6:7]
	global_load_dword v92, v[2:3], off
	v_lshl_add_u64 v[2:3], v[2:3], 0, s[6:7]
	global_load_dword v93, v[2:3], off
	v_lshl_add_u64 v[2:3], v[2:3], 0, s[6:7]
	global_load_dword v94, v[2:3], off
	v_lshl_add_u64 v[2:3], v[2:3], 0, s[6:7]
	global_load_dword v95, v[2:3], off
	v_lshl_add_u64 v[2:3], v[2:3], 0, s[6:7]
	global_load_dword v96, v[2:3], off
	v_lshl_add_u64 v[2:3], v[2:3], 0, s[6:7]
	global_load_dword v97, v[2:3], off
	v_lshl_add_u64 v[2:3], v[2:3], 0, s[6:7]
	global_load_dword v98, v[2:3], off
	v_lshl_add_u64 v[2:3], v[2:3], 0, s[6:7]
	global_load_dword v99, v[2:3], off
	v_lshl_add_u64 v[2:3], v[2:3], 0, s[6:7]
	global_load_dword v100, v[2:3], off
	v_lshl_add_u64 v[2:3], v[2:3], 0, s[6:7]
	global_load_dword v101, v[2:3], off
	v_lshl_add_u64 v[2:3], v[2:3], 0, s[6:7]
	global_load_dword v102, v[2:3], off
	v_lshl_add_u64 v[2:3], v[2:3], 0, s[6:7]
	global_load_dword v103, v[2:3], off
	v_lshl_add_u64 v[2:3], v[2:3], 0, s[6:7]
	global_load_dword v104, v[2:3], off
	v_lshl_add_u64 v[2:3], v[2:3], 0, s[6:7]
	global_load_dword v105, v[2:3], off
	v_lshl_add_u64 v[2:3], v[2:3], 0, s[6:7]
	global_load_dword v106, v[2:3], off
	v_lshl_add_u64 v[2:3], v[2:3], 0, s[6:7]
	global_load_dword v107, v[2:3], off
	v_lshl_add_u64 v[2:3], v[2:3], 0, s[6:7]
	global_load_dword v108, v[2:3], off
	v_lshl_add_u64 v[2:3], v[2:3], 0, s[6:7]
	global_load_dword v109, v[2:3], off
	v_lshl_add_u64 v[2:3], v[2:3], 0, s[6:7]
	global_load_dword v110, v[2:3], off
	v_lshl_add_u64 v[2:3], v[2:3], 0, s[6:7]
	global_load_dword v111, v[2:3], off
	v_lshl_add_u64 v[2:3], v[2:3], 0, s[6:7]
	s_mov_b32 vcc_lo, 4
; __device__ __forceinline__ void prep_mod_job(const Params& p, int m, float* sm) {
;     ...
;   for (int k = 0; k < 256; ++k) {
;     float w = wp[(size_t)k * 9216];
; #pragma unroll
;     for (int s = 0; s < 8; ++s) acc[s] += scp[s * 1024 + k] * w;
;   }
.Lpm_loop:
	s_waitcnt vmcnt(32)
	ds_read_b128 v[128:131], v4 offset:0
	ds_read_b128 v[132:135], v4 offset:4096
	ds_read_b128 v[136:139], v4 offset:8192
	ds_read_b128 v[140:143], v4 offset:12288
	ds_read_b128 v[144:147], v4 offset:16384
	ds_read_b128 v[148:151], v4 offset:20480
	ds_read_b128 v[152:155], v4 offset:24576
	ds_read_b128 v[156:159], v4 offset:28672
	s_waitcnt lgkmcnt(4)
	ds_read_b128 v[160:163], v4 offset:16
	ds_read_b128 v[164:167], v4 offset:4112
	ds_read_b128 v[168:171], v4 offset:8208
	ds_read_b128 v[172:175], v4 offset:12304
	ds_read_b128 v[176:179], v4 offset:16400
	ds_read_b128 v[180:183], v4 offset:20496
	ds_read_b128 v[184:187], v4 offset:24592
	ds_read_b128 v[188:191], v4 offset:28688
	s_waitcnt lgkmcnt(8)
	v_fmac_f32_e32 v22, v64, v128
	v_fmac_f32_e32 v23, v64, v132
	v_fmac_f32_e32 v24, v64, v136
	v_fmac_f32_e32 v25, v64, v140
	v_fmac_f32_e32 v26, v64, v144
	v_fmac_f32_e32 v27, v64, v148
	v_fmac_f32_e32 v20, v64, v152
	v_fmac_f32_e32 v21, v64, v156
	v_fmac_f32_e32 v22, v65, v129
	v_fmac_f32_e32 v23, v65, v133
	v_fmac_f32_e32 v24, v65, v137
	v_fmac_f32_e32 v25, v65, v141
	v_fmac_f32_e32 v26, v65, v145
	v_fmac_f32_e32 v27, v65, v149
	v_fmac_f32_e32 v20, v65, v153
	v_fmac_f32_e32 v21, v65, v157
	v_fmac_f32_e32 v22, v66, v130
	v_fmac_f32_e32 v23, v66, v134
	v_fmac_f32_e32 v24, v66, v138
	v_fmac_f32_e32 v25, v66, v142
	v_fmac_f32_e32 v26, v66, v146
	v_fmac_f32_e32 v27, v66, v150
	v_fmac_f32_e32 v20, v66, v154
	v_fmac_f32_e32 v21, v66, v158
	v_fmac_f32_e32 v22, v67, v131
	v_fmac_f32_e32 v23, v67, v135
	v_fmac_f32_e32 v24, v67, v139
	v_fmac_f32_e32 v25, v67, v143
	v_fmac_f32_e32 v26, v67, v147
	v_fmac_f32_e32 v27, v67, v151
	v_fmac_f32_e32 v20, v67, v155
	v_fmac_f32_e32 v21, v67, v159
	s_waitcnt lgkmcnt(4)
	ds_read_b128 v[128:131], v4 offset:32
	ds_read_b128 v[132:135], v4 offset:4128
	ds_read_b128 v[136:139], v4 offset:8224
	ds_read_b128 v[140:143], v4 offset:12320
	ds_read_b128 v[144:147], v4 offset:16416
	ds_read_b128 v[148:151], v4 offset:20512
	ds_read_b128 v[152:155], v4 offset:24608
	ds_read_b128 v[156:159], v4 offset:28704
	s_waitcnt lgkmcnt(8)
	v_fmac_f32_e32 v22, v68, v160
	v_fmac_f32_e32 v23, v68, v164
	v_fmac_f32_e32 v24, v68, v168
	v_fmac_f32_e32 v25, v68, v172
	v_fmac_f32_e32 v26, v68, v176
	v_fmac_f32_e32 v27, v68, v180
	v_fmac_f32_e32 v20, v68, v184
	v_fmac_f32_e32 v21, v68, v188
	v_fmac_f32_e32 v22, v69, v161
	v_fmac_f32_e32 v23, v69, v165
	v_fmac_f32_e32 v24, v69, v169
	v_fmac_f32_e32 v25, v69, v173
	v_fmac_f32_e32 v26, v69, v177
	v_fmac_f32_e32 v27, v69, v181
	v_fmac_f32_e32 v20, v69, v185
	v_fmac_f32_e32 v21, v69, v189
	v_fmac_f32_e32 v22, v70, v162
	v_fmac_f32_e32 v23, v70, v166
	v_fmac_f32_e32 v24, v70, v170
	v_fmac_f32_e32 v25, v70, v174
	v_fmac_f32_e32 v26, v70, v178
	v_fmac_f32_e32 v27, v70, v182
	v_fmac_f32_e32 v20, v70, v186
	v_fmac_f32_e32 v21, v70, v190
	v_fmac_f32_e32 v22, v71, v163
	v_fmac_f32_e32 v23, v71, v167
	v_fmac_f32_e32 v24, v71, v171
	v_fmac_f32_e32 v25, v71, v175
	v_fmac_f32_e32 v26, v71, v179
	v_fmac_f32_e32 v27, v71, v183
	v_fmac_f32_e32 v20, v71, v187
	v_fmac_f32_e32 v21, v71, v191
	s_waitcnt lgkmcnt(4)
	ds_read_b128 v[160:163], v4 offset:48
	ds_read_b128 v[164:167], v4 offset:4144
	ds_read_b128 v[168:171], v4 offset:8240
	ds_read_b128 v[172:175], v4 offset:12336
	ds_read_b128 v[176:179], v4 offset:16432
	ds_read_b128 v[180:183], v4 offset:20528
	ds_read_b128 v[184:187], v4 offset:24624
	ds_read_b128 v[188:191], v4 offset:28720
	s_waitcnt lgkmcnt(8)
	v_fmac_f32_e32 v22, v72, v128
	v_fmac_f32_e32 v23, v72, v132
	v_fmac_f32_e32 v24, v72, v136
	v_fmac_f32_e32 v25, v72, v140
	v_fmac_f32_e32 v26, v72, v144
	v_fmac_f32_e32 v27, v72, v148
	v_fmac_f32_e32 v20, v72, v152
	v_fmac_f32_e32 v21, v72, v156
	v_fmac_f32_e32 v22, v73, v129
	v_fmac_f32_e32 v23, v73, v133
	v_fmac_f32_e32 v24, v73, v137
	v_fmac_f32_e32 v25, v73, v141
	v_fmac_f32_e32 v26, v73, v145
	v_fmac_f32_e32 v27, v73, v149
	v_fmac_f32_e32 v20, v73, v153
	v_fmac_f32_e32 v21, v73, v157
	v_fmac_f32_e32 v22, v74, v130
	v_fmac_f32_e32 v23, v74, v134
	v_fmac_f32_e32 v24, v74, v138
	v_fmac_f32_e32 v25, v74, v142
	v_fmac_f32_e32 v26, v74, v146
	v_fmac_f32_e32 v27, v74, v150
	v_fmac_f32_e32 v20, v74, v154
	v_fmac_f32_e32 v21, v74, v158
	v_fmac_f32_e32 v22, v75, v131
	v_fmac_f32_e32 v23, v75, v135
	v_fmac_f32_e32 v24, v75, v139
	v_fmac_f32_e32 v25, v75, v143
	v_fmac_f32_e32 v26, v75, v147
	v_fmac_f32_e32 v27, v75, v151
	v_fmac_f32_e32 v20, v75, v155
	v_fmac_f32_e32 v21, v75, v159
	s_waitcnt lgkmcnt(0)
	v_fmac_f32_e32 v22, v76, v160
	v_fmac_f32_e32 v23, v76, v164
	v_fmac_f32_e32 v24, v76, v168
	v_fmac_f32_e32 v25, v76, v172
	v_fmac_f32_e32 v26, v76, v176
	v_fmac_f32_e32 v27, v76, v180
	v_fmac_f32_e32 v20, v76, v184
	v_fmac_f32_e32 v21, v76, v188
	v_fmac_f32_e32 v22, v77, v161
	v_fmac_f32_e32 v23, v77, v165
	v_fmac_f32_e32 v24, v77, v169
	v_fmac_f32_e32 v25, v77, v173
	v_fmac_f32_e32 v26, v77, v177
	v_fmac_f32_e32 v27, v77, v181
	v_fmac_f32_e32 v20, v77, v185
	v_fmac_f32_e32 v21, v77, v189
	v_fmac_f32_e32 v22, v78, v162
	v_fmac_f32_e32 v23, v78, v166
	v_fmac_f32_e32 v24, v78, v170
	v_fmac_f32_e32 v25, v78, v174
	v_fmac_f32_e32 v26, v78, v178
	v_fmac_f32_e32 v27, v78, v182
	v_fmac_f32_e32 v20, v78, v186
	v_fmac_f32_e32 v21, v78, v190
	v_fmac_f32_e32 v22, v79, v163
	v_fmac_f32_e32 v23, v79, v167
	v_fmac_f32_e32 v24, v79, v171
	v_fmac_f32_e32 v25, v79, v175
	v_fmac_f32_e32 v26, v79, v179
	v_fmac_f32_e32 v27, v79, v183
	v_fmac_f32_e32 v20, v79, v187
	v_fmac_f32_e32 v21, v79, v191
	global_load_dword v112, v[2:3], off
	v_lshl_add_u64 v[2:3], v[2:3], 0, s[6:7]
	global_load_dword v113, v[2:3], off
	v_lshl_add_u64 v[2:3], v[2:3], 0, s[6:7]
	global_load_dword v114, v[2:3], off
	v_lshl_add_u64 v[2:3], v[2:3], 0, s[6:7]
	global_load_dword v115, v[2:3], off
	v_lshl_add_u64 v[2:3], v[2:3], 0, s[6:7]
	global_load_dword v116, v[2:3], off
	v_lshl_add_u64 v[2:3], v[2:3], 0, s[6:7]
	global_load_dword v117, v[2:3], off
	v_lshl_add_u64 v[2:3], v[2:3], 0, s[6:7]
	global_load_dword v118, v[2:3], off
	v_lshl_add_u64 v[2:3], v[2:3], 0, s[6:7]
	global_load_dword v119, v[2:3], off
	v_lshl_add_u64 v[2:3], v[2:3], 0, s[6:7]
	global_load_dword v120, v[2:3], off
	v_lshl_add_u64 v[2:3], v[2:3], 0, s[6:7]
	global_load_dword v121, v[2:3], off
	v_lshl_add_u64 v[2:3], v[2:3], 0, s[6:7]
	global_load_dword v122, v[2:3], off
	v_lshl_add_u64 v[2:3], v[2:3], 0, s[6:7]
	global_load_dword v123, v[2:3], off
	v_lshl_add_u64 v[2:3], v[2:3], 0, s[6:7]
	global_load_dword v124, v[2:3], off
	v_lshl_add_u64 v[2:3], v[2:3], 0, s[6:7]
	global_load_dword v125, v[2:3], off
	v_lshl_add_u64 v[2:3], v[2:3], 0, s[6:7]
	global_load_dword v126, v[2:3], off
	v_lshl_add_u64 v[2:3], v[2:3], 0, s[6:7]
	global_load_dword v127, v[2:3], off
	v_lshl_add_u64 v[2:3], v[2:3], 0, s[6:7]
	s_waitcnt vmcnt(32)
; __device__ __forceinline__ void prep_mod_job(const Params& p, int m, float* sm) {
;     ...
;   for (int k = 0; k < 256; ++k) {
;     float w = wp[(size_t)k * 9216];
; #pragma unroll
;     for (int s = 0; s < 8; ++s) acc[s] += scp[s * 1024 + k] * w;
;   }
	ds_read_b128 v[128:131], v4 offset:64
	ds_read_b128 v[132:135], v4 offset:4160
	ds_read_b128 v[136:139], v4 offset:8256
	ds_read_b128 v[140:143], v4 offset:12352
	ds_read_b128 v[144:147], v4 offset:16448
	ds_read_b128 v[148:151], v4 offset:20544
	ds_read_b128 v[152:155], v4 offset:24640
	ds_read_b128 v[156:159], v4 offset:28736
	s_waitcnt lgkmcnt(4)
	ds_read_b128 v[160:163], v4 offset:80
	ds_read_b128 v[164:167], v4 offset:4176
	ds_read_b128 v[168:171], v4 offset:8272
	ds_read_b128 v[172:175], v4 offset:12368
	ds_read_b128 v[176:179], v4 offset:16464
	ds_read_b128 v[180:183], v4 offset:20560
	ds_read_b128 v[184:187], v4 offset:24656
	ds_read_b128 v[188:191], v4 offset:28752
	s_waitcnt lgkmcnt(8)
	v_fmac_f32_e32 v22, v80, v128
	v_fmac_f32_e32 v23, v80, v132
	v_fmac_f32_e32 v24, v80, v136
	v_fmac_f32_e32 v25, v80, v140
	v_fmac_f32_e32 v26, v80, v144
	v_fmac_f32_e32 v27, v80, v148
	v_fmac_f32_e32 v20, v80, v152
	v_fmac_f32_e32 v21, v80, v156
	v_fmac_f32_e32 v22, v81, v129
	v_fmac_f32_e32 v23, v81, v133
	v_fmac_f32_e32 v24, v81, v137
	v_fmac_f32_e32 v25, v81, v141
	v_fmac_f32_e32 v26, v81, v145
	v_fmac_f32_e32 v27, v81, v149
	v_fmac_f32_e32 v20, v81, v153
	v_fmac_f32_e32 v21, v81, v157
	v_fmac_f32_e32 v22, v82, v130
	v_fmac_f32_e32 v23, v82, v134
	v_fmac_f32_e32 v24, v82, v138
	v_fmac_f32_e32 v25, v82, v142
	v_fmac_f32_e32 v26, v82, v146
	v_fmac_f32_e32 v27, v82, v150
	v_fmac_f32_e32 v20, v82, v154
	v_fmac_f32_e32 v21, v82, v158
	v_fmac_f32_e32 v22, v83, v131
	v_fmac_f32_e32 v23, v83, v135
	v_fmac_f32_e32 v24, v83, v139
	v_fmac_f32_e32 v25, v83, v143
	v_fmac_f32_e32 v26, v83, v147
	v_fmac_f32_e32 v27, v83, v151
	v_fmac_f32_e32 v20, v83, v155
	v_fmac_f32_e32 v21, v83, v159
	s_waitcnt lgkmcnt(4)
	ds_read_b128 v[128:131], v4 offset:96
	ds_read_b128 v[132:135], v4 offset:4192
	ds_read_b128 v[136:139], v4 offset:8288
	ds_read_b128 v[140:143], v4 offset:12384
	ds_read_b128 v[144:147], v4 offset:16480
	ds_read_b128 v[148:151], v4 offset:20576
	ds_read_b128 v[152:155], v4 offset:24672
	ds_read_b128 v[156:159], v4 offset:28768
	s_waitcnt lgkmcnt(8)
	v_fmac_f32_e32 v22, v84, v160
	v_fmac_f32_e32 v23, v84, v164
	v_fmac_f32_e32 v24, v84, v168
	v_fmac_f32_e32 v25, v84, v172
	v_fmac_f32_e32 v26, v84, v176
	v_fmac_f32_e32 v27, v84, v180
	v_fmac_f32_e32 v20, v84, v184
	v_fmac_f32_e32 v21, v84, v188
	v_fmac_f32_e32 v22, v85, v161
	v_fmac_f32_e32 v23, v85, v165
	v_fmac_f32_e32 v24, v85, v169
	v_fmac_f32_e32 v25, v85, v173
	v_fmac_f32_e32 v26, v85, v177
	v_fmac_f32_e32 v27, v85, v181
	v_fmac_f32_e32 v20, v85, v185
	v_fmac_f32_e32 v21, v85, v189
	v_fmac_f32_e32 v22, v86, v162
	v_fmac_f32_e32 v23, v86, v166
	v_fmac_f32_e32 v24, v86, v170
	v_fmac_f32_e32 v25, v86, v174
	v_fmac_f32_e32 v26, v86, v178
	v_fmac_f32_e32 v27, v86, v182
	v_fmac_f32_e32 v20, v86, v186
	v_fmac_f32_e32 v21, v86, v190
	v_fmac_f32_e32 v22, v87, v163
	v_fmac_f32_e32 v23, v87, v167
	v_fmac_f32_e32 v24, v87, v171
	v_fmac_f32_e32 v25, v87, v175
	v_fmac_f32_e32 v26, v87, v179
	v_fmac_f32_e32 v27, v87, v183
	v_fmac_f32_e32 v20, v87, v187
	v_fmac_f32_e32 v21, v87, v191
	s_waitcnt lgkmcnt(4)
	ds_read_b128 v[160:163], v4 offset:112
	ds_read_b128 v[164:167], v4 offset:4208
	ds_read_b128 v[168:171], v4 offset:8304
	ds_read_b128 v[172:175], v4 offset:12400
	ds_read_b128 v[176:179], v4 offset:16496
	ds_read_b128 v[180:183], v4 offset:20592
	ds_read_b128 v[184:187], v4 offset:24688
	ds_read_b128 v[188:191], v4 offset:28784
	s_waitcnt lgkmcnt(8)
	v_fmac_f32_e32 v22, v88, v128
	v_fmac_f32_e32 v23, v88, v132
	v_fmac_f32_e32 v24, v88, v136
	v_fmac_f32_e32 v25, v88, v140
	v_fmac_f32_e32 v26, v88, v144
	v_fmac_f32_e32 v27, v88, v148
	v_fmac_f32_e32 v20, v88, v152
	v_fmac_f32_e32 v21, v88, v156
	v_fmac_f32_e32 v22, v89, v129
	v_fmac_f32_e32 v23, v89, v133
	v_fmac_f32_e32 v24, v89, v137
	v_fmac_f32_e32 v25, v89, v141
	v_fmac_f32_e32 v26, v89, v145
	v_fmac_f32_e32 v27, v89, v149
	v_fmac_f32_e32 v20, v89, v153
	v_fmac_f32_e32 v21, v89, v157
	v_fmac_f32_e32 v22, v90, v130
	v_fmac_f32_e32 v23, v90, v134
	v_fmac_f32_e32 v24, v90, v138
	v_fmac_f32_e32 v25, v90, v142
	v_fmac_f32_e32 v26, v90, v146
	v_fmac_f32_e32 v27, v90, v150
	v_fmac_f32_e32 v20, v90, v154
	v_fmac_f32_e32 v21, v90, v158
	v_fmac_f32_e32 v22, v91, v131
	v_fmac_f32_e32 v23, v91, v135
	v_fmac_f32_e32 v24, v91, v139
	v_fmac_f32_e32 v25, v91, v143
	v_fmac_f32_e32 v26, v91, v147
	v_fmac_f32_e32 v27, v91, v151
	v_fmac_f32_e32 v20, v91, v155
	v_fmac_f32_e32 v21, v91, v159
	s_waitcnt lgkmcnt(0)
	v_fmac_f32_e32 v22, v92, v160
	v_fmac_f32_e32 v23, v92, v164
	v_fmac_f32_e32 v24, v92, v168
	v_fmac_f32_e32 v25, v92, v172
	v_fmac_f32_e32 v26, v92, v176
	v_fmac_f32_e32 v27, v92, v180
	v_fmac_f32_e32 v20, v92, v184
	v_fmac_f32_e32 v21, v92, v188
	v_fmac_f32_e32 v22, v93, v161
	v_fmac_f32_e32 v23, v93, v165
	v_fmac_f32_e32 v24, v93, v169
	v_fmac_f32_e32 v25, v93, v173
	v_fmac_f32_e32 v26, v93, v177
	v_fmac_f32_e32 v27, v93, v181
	v_fmac_f32_e32 v20, v93, v185
	v_fmac_f32_e32 v21, v93, v189
	v_fmac_f32_e32 v22, v94, v162
	v_fmac_f32_e32 v23, v94, v166
	v_fmac_f32_e32 v24, v94, v170
	v_fmac_f32_e32 v25, v94, v174
	v_fmac_f32_e32 v26, v94, v178
	v_fmac_f32_e32 v27, v94, v182
	v_fmac_f32_e32 v20, v94, v186
	v_fmac_f32_e32 v21, v94, v190
	v_fmac_f32_e32 v22, v95, v163
	v_fmac_f32_e32 v23, v95, v167
	v_fmac_f32_e32 v24, v95, v171
	v_fmac_f32_e32 v25, v95, v175
	v_fmac_f32_e32 v26, v95, v179
	v_fmac_f32_e32 v27, v95, v183
	v_fmac_f32_e32 v20, v95, v187
	v_fmac_f32_e32 v21, v95, v191
	s_cmp_eq_u32 vcc_lo, 1
	s_cbranch_scc1 .Lpm_s2l
	global_load_dword v64, v[2:3], off
	v_lshl_add_u64 v[2:3], v[2:3], 0, s[6:7]
	global_load_dword v65, v[2:3], off
	v_lshl_add_u64 v[2:3], v[2:3], 0, s[6:7]
	global_load_dword v66, v[2:3], off
	v_lshl_add_u64 v[2:3], v[2:3], 0, s[6:7]
	global_load_dword v67, v[2:3], off
	v_lshl_add_u64 v[2:3], v[2:3], 0, s[6:7]
	global_load_dword v68, v[2:3], off
	v_lshl_add_u64 v[2:3], v[2:3], 0, s[6:7]
	global_load_dword v69, v[2:3], off
	v_lshl_add_u64 v[2:3], v[2:3], 0, s[6:7]
	global_load_dword v70, v[2:3], off
	v_lshl_add_u64 v[2:3], v[2:3], 0, s[6:7]
	global_load_dword v71, v[2:3], off
	v_lshl_add_u64 v[2:3], v[2:3], 0, s[6:7]
	global_load_dword v72, v[2:3], off
	v_lshl_add_u64 v[2:3], v[2:3], 0, s[6:7]
	global_load_dword v73, v[2:3], off
	v_lshl_add_u64 v[2:3], v[2:3], 0, s[6:7]
	global_load_dword v74, v[2:3], off
	v_lshl_add_u64 v[2:3], v[2:3], 0, s[6:7]
	global_load_dword v75, v[2:3], off
	v_lshl_add_u64 v[2:3], v[2:3], 0, s[6:7]
	global_load_dword v76, v[2:3], off
	v_lshl_add_u64 v[2:3], v[2:3], 0, s[6:7]
	global_load_dword v77, v[2:3], off
	v_lshl_add_u64 v[2:3], v[2:3], 0, s[6:7]
	global_load_dword v78, v[2:3], off
	v_lshl_add_u64 v[2:3], v[2:3], 0, s[6:7]
	global_load_dword v79, v[2:3], off
	v_lshl_add_u64 v[2:3], v[2:3], 0, s[6:7]
	s_waitcnt vmcnt(32)
	s_branch .Lpm_s2c
; __device__ __forceinline__ void prep_mod_job(const Params& p, int m, float* sm) {
;     ...
;   for (int k = 0; k < 256; ++k) {
;     float w = wp[(size_t)k * 9216];
; #pragma unroll
;     for (int s = 0; s < 8; ++s) acc[s] += scp[s * 1024 + k] * w;
;   }
.Lpm_s2l:
	s_waitcnt vmcnt(16)
.Lpm_s2c:
	ds_read_b128 v[128:131], v4 offset:128
	ds_read_b128 v[132:135], v4 offset:4224
	ds_read_b128 v[136:139], v4 offset:8320
	ds_read_b128 v[140:143], v4 offset:12416
	ds_read_b128 v[144:147], v4 offset:16512
	ds_read_b128 v[148:151], v4 offset:20608
	ds_read_b128 v[152:155], v4 offset:24704
	ds_read_b128 v[156:159], v4 offset:28800
	s_waitcnt lgkmcnt(4)
	ds_read_b128 v[160:163], v4 offset:144
	ds_read_b128 v[164:167], v4 offset:4240
	ds_read_b128 v[168:171], v4 offset:8336
	ds_read_b128 v[172:175], v4 offset:12432
	ds_read_b128 v[176:179], v4 offset:16528
	ds_read_b128 v[180:183], v4 offset:20624
	ds_read_b128 v[184:187], v4 offset:24720
	ds_read_b128 v[188:191], v4 offset:28816
	s_waitcnt lgkmcnt(8)
	v_fmac_f32_e32 v22, v96, v128
	v_fmac_f32_e32 v23, v96, v132
	v_fmac_f32_e32 v24, v96, v136
	v_fmac_f32_e32 v25, v96, v140
	v_fmac_f32_e32 v26, v96, v144
	v_fmac_f32_e32 v27, v96, v148
	v_fmac_f32_e32 v20, v96, v152
	v_fmac_f32_e32 v21, v96, v156
	v_fmac_f32_e32 v22, v97, v129
	v_fmac_f32_e32 v23, v97, v133
	v_fmac_f32_e32 v24, v97, v137
	v_fmac_f32_e32 v25, v97, v141
	v_fmac_f32_e32 v26, v97, v145
	v_fmac_f32_e32 v27, v97, v149
	v_fmac_f32_e32 v20, v97, v153
	v_fmac_f32_e32 v21, v97, v157
	v_fmac_f32_e32 v22, v98, v130
	v_fmac_f32_e32 v23, v98, v134
	v_fmac_f32_e32 v24, v98, v138
	v_fmac_f32_e32 v25, v98, v142
	v_fmac_f32_e32 v26, v98, v146
	v_fmac_f32_e32 v27, v98, v150
	v_fmac_f32_e32 v20, v98, v154
	v_fmac_f32_e32 v21, v98, v158
	v_fmac_f32_e32 v22, v99, v131
	v_fmac_f32_e32 v23, v99, v135
	v_fmac_f32_e32 v24, v99, v139
	v_fmac_f32_e32 v25, v99, v143
	v_fmac_f32_e32 v26, v99, v147
	v_fmac_f32_e32 v27, v99, v151
	v_fmac_f32_e32 v20, v99, v155
	v_fmac_f32_e32 v21, v99, v159
	s_waitcnt lgkmcnt(4)
	ds_read_b128 v[128:131], v4 offset:160
	ds_read_b128 v[132:135], v4 offset:4256
	ds_read_b128 v[136:139], v4 offset:8352
	ds_read_b128 v[140:143], v4 offset:12448
	ds_read_b128 v[144:147], v4 offset:16544
	ds_read_b128 v[148:151], v4 offset:20640
	ds_read_b128 v[152:155], v4 offset:24736
	ds_read_b128 v[156:159], v4 offset:28832
	s_waitcnt lgkmcnt(8)
	v_fmac_f32_e32 v22, v100, v160
	v_fmac_f32_e32 v23, v100, v164
	v_fmac_f32_e32 v24, v100, v168
	v_fmac_f32_e32 v25, v100, v172
	v_fmac_f32_e32 v26, v100, v176
	v_fmac_f32_e32 v27, v100, v180
	v_fmac_f32_e32 v20, v100, v184
	v_fmac_f32_e32 v21, v100, v188
	v_fmac_f32_e32 v22, v101, v161
	v_fmac_f32_e32 v23, v101, v165
	v_fmac_f32_e32 v24, v101, v169
	v_fmac_f32_e32 v25, v101, v173
	v_fmac_f32_e32 v26, v101, v177
	v_fmac_f32_e32 v27, v101, v181
	v_fmac_f32_e32 v20, v101, v185
	v_fmac_f32_e32 v21, v101, v189
	v_fmac_f32_e32 v22, v102, v162
	v_fmac_f32_e32 v23, v102, v166
	v_fmac_f32_e32 v24, v102, v170
	v_fmac_f32_e32 v25, v102, v174
	v_fmac_f32_e32 v26, v102, v178
	v_fmac_f32_e32 v27, v102, v182
	v_fmac_f32_e32 v20, v102, v186
	v_fmac_f32_e32 v21, v102, v190
	v_fmac_f32_e32 v22, v103, v163
	v_fmac_f32_e32 v23, v103, v167
	v_fmac_f32_e32 v24, v103, v171
	v_fmac_f32_e32 v25, v103, v175
	v_fmac_f32_e32 v26, v103, v179
	v_fmac_f32_e32 v27, v103, v183
	v_fmac_f32_e32 v20, v103, v187
	v_fmac_f32_e32 v21, v103, v191
	s_waitcnt lgkmcnt(4)
	ds_read_b128 v[160:163], v4 offset:176
	ds_read_b128 v[164:167], v4 offset:4272
	ds_read_b128 v[168:171], v4 offset:8368
	ds_read_b128 v[172:175], v4 offset:12464
	ds_read_b128 v[176:179], v4 offset:16560
	ds_read_b128 v[180:183], v4 offset:20656
	ds_read_b128 v[184:187], v4 offset:24752
	ds_read_b128 v[188:191], v4 offset:28848
	s_waitcnt lgkmcnt(8)
	v_fmac_f32_e32 v22, v104, v128
	v_fmac_f32_e32 v23, v104, v132
	v_fmac_f32_e32 v24, v104, v136
	v_fmac_f32_e32 v25, v104, v140
	v_fmac_f32_e32 v26, v104, v144
	v_fmac_f32_e32 v27, v104, v148
	v_fmac_f32_e32 v20, v104, v152
	v_fmac_f32_e32 v21, v104, v156
	v_fmac_f32_e32 v22, v105, v129
	v_fmac_f32_e32 v23, v105, v133
	v_fmac_f32_e32 v24, v105, v137
	v_fmac_f32_e32 v25, v105, v141
	v_fmac_f32_e32 v26, v105, v145
	v_fmac_f32_e32 v27, v105, v149
	v_fmac_f32_e32 v20, v105, v153
	v_fmac_f32_e32 v21, v105, v157
	v_fmac_f32_e32 v22, v106, v130
	v_fmac_f32_e32 v23, v106, v134
	v_fmac_f32_e32 v24, v106, v138
	v_fmac_f32_e32 v25, v106, v142
	v_fmac_f32_e32 v26, v106, v146
	v_fmac_f32_e32 v27, v106, v150
	v_fmac_f32_e32 v20, v106, v154
	v_fmac_f32_e32 v21, v106, v158
	v_fmac_f32_e32 v22, v107, v131
	v_fmac_f32_e32 v23, v107, v135
	v_fmac_f32_e32 v24, v107, v139
	v_fmac_f32_e32 v25, v107, v143
	v_fmac_f32_e32 v26, v107, v147
	v_fmac_f32_e32 v27, v107, v151
	v_fmac_f32_e32 v20, v107, v155
	v_fmac_f32_e32 v21, v107, v159
	s_waitcnt lgkmcnt(0)
	v_fmac_f32_e32 v22, v108, v160
	v_fmac_f32_e32 v23, v108, v164
	v_fmac_f32_e32 v24, v108, v168
	v_fmac_f32_e32 v25, v108, v172
	v_fmac_f32_e32 v26, v108, v176
	v_fmac_f32_e32 v27, v108, v180
	v_fmac_f32_e32 v20, v108, v184
	v_fmac_f32_e32 v21, v108, v188
	v_fmac_f32_e32 v22, v109, v161
	v_fmac_f32_e32 v23, v109, v165
	v_fmac_f32_e32 v24, v109, v169
	v_fmac_f32_e32 v25, v109, v173
	v_fmac_f32_e32 v26, v109, v177
	v_fmac_f32_e32 v27, v109, v181
	v_fmac_f32_e32 v20, v109, v185
	v_fmac_f32_e32 v21, v109, v189
	v_fmac_f32_e32 v22, v110, v162
	v_fmac_f32_e32 v23, v110, v166
	v_fmac_f32_e32 v24, v110, v170
	v_fmac_f32_e32 v25, v110, v174
	v_fmac_f32_e32 v26, v110, v178
	v_fmac_f32_e32 v27, v110, v182
	v_fmac_f32_e32 v20, v110, v186
	v_fmac_f32_e32 v21, v110, v190
	v_fmac_f32_e32 v22, v111, v163
	v_fmac_f32_e32 v23, v111, v167
	v_fmac_f32_e32 v24, v111, v171
	v_fmac_f32_e32 v25, v111, v175
	v_fmac_f32_e32 v26, v111, v179
	v_fmac_f32_e32 v27, v111, v183
	v_fmac_f32_e32 v20, v111, v187
	v_fmac_f32_e32 v21, v111, v191
	s_cmp_eq_u32 vcc_lo, 1
	s_cbranch_scc1 .Lpm_s3l
	global_load_dword v80, v[2:3], off
	v_lshl_add_u64 v[2:3], v[2:3], 0, s[6:7]
	global_load_dword v81, v[2:3], off
	v_lshl_add_u64 v[2:3], v[2:3], 0, s[6:7]
	global_load_dword v82, v[2:3], off
	v_lshl_add_u64 v[2:3], v[2:3], 0, s[6:7]
	global_load_dword v83, v[2:3], off
	v_lshl_add_u64 v[2:3], v[2:3], 0, s[6:7]
	global_load_dword v84, v[2:3], off
	v_lshl_add_u64 v[2:3], v[2:3], 0, s[6:7]
	global_load_dword v85, v[2:3], off
	v_lshl_add_u64 v[2:3], v[2:3], 0, s[6:7]
	global_load_dword v86, v[2:3], off
	v_lshl_add_u64 v[2:3], v[2:3], 0, s[6:7]
	global_load_dword v87, v[2:3], off
	v_lshl_add_u64 v[2:3], v[2:3], 0, s[6:7]
	global_load_dword v88, v[2:3], off
	v_lshl_add_u64 v[2:3], v[2:3], 0, s[6:7]
	global_load_dword v89, v[2:3], off
	v_lshl_add_u64 v[2:3], v[2:3], 0, s[6:7]
	global_load_dword v90, v[2:3], off
	v_lshl_add_u64 v[2:3], v[2:3], 0, s[6:7]
	global_load_dword v91, v[2:3], off
	v_lshl_add_u64 v[2:3], v[2:3], 0, s[6:7]
	global_load_dword v92, v[2:3], off
	v_lshl_add_u64 v[2:3], v[2:3], 0, s[6:7]
	global_load_dword v93, v[2:3], off
	v_lshl_add_u64 v[2:3], v[2:3], 0, s[6:7]
	global_load_dword v94, v[2:3], off
	v_lshl_add_u64 v[2:3], v[2:3], 0, s[6:7]
	global_load_dword v95, v[2:3], off
	v_lshl_add_u64 v[2:3], v[2:3], 0, s[6:7]
	s_waitcnt vmcnt(32)
	s_branch .Lpm_s3c

; __device__ __forceinline__ void prep_mod_job(const Params& p, int m, float* sm) {
;     ...
;   for (int k = 0; k < 256; ++k) {
;     float w = wp[(size_t)k * 9216];
; #pragma unroll
;     for (int s = 0; s < 8; ++s) acc[s] += scp[s * 1024 + k] * w;
;   }
.Lpm_s3c:
	ds_read_b128 v[128:131], v4 offset:192
	ds_read_b128 v[132:135], v4 offset:4288
	ds_read_b128 v[136:139], v4 offset:8384
	ds_read_b128 v[140:143], v4 offset:12480
	ds_read_b128 v[144:147], v4 offset:16576
	ds_read_b128 v[148:151], v4 offset:20672
	ds_read_b128 v[152:155], v4 offset:24768
	ds_read_b128 v[156:159], v4 offset:28864
	s_waitcnt lgkmcnt(4)
	ds_read_b128 v[160:163], v4 offset:208
	ds_read_b128 v[164:167], v4 offset:4304
	ds_read_b128 v[168:171], v4 offset:8400
	ds_read_b128 v[172:175], v4 offset:12496
	ds_read_b128 v[176:179], v4 offset:16592
	ds_read_b128 v[180:183], v4 offset:20688
	ds_read_b128 v[184:187], v4 offset:24784
	ds_read_b128 v[188:191], v4 offset:28880
	s_waitcnt lgkmcnt(8)
	v_fmac_f32_e32 v22, v112, v128
	v_fmac_f32_e32 v23, v112, v132
	v_fmac_f32_e32 v24, v112, v136
	v_fmac_f32_e32 v25, v112, v140
	v_fmac_f32_e32 v26, v112, v144
	v_fmac_f32_e32 v27, v112, v148
	v_fmac_f32_e32 v20, v112, v152
	v_fmac_f32_e32 v21, v112, v156
	v_fmac_f32_e32 v22, v113, v129
	v_fmac_f32_e32 v23, v113, v133
	v_fmac_f32_e32 v24, v113, v137
	v_fmac_f32_e32 v25, v113, v141
	v_fmac_f32_e32 v26, v113, v145
	v_fmac_f32_e32 v27, v113, v149
	v_fmac_f32_e32 v20, v113, v153
	v_fmac_f32_e32 v21, v113, v157
	v_fmac_f32_e32 v22, v114, v130
	v_fmac_f32_e32 v23, v114, v134
	v_fmac_f32_e32 v24, v114, v138
	v_fmac_f32_e32 v25, v114, v142
	v_fmac_f32_e32 v26, v114, v146
	v_fmac_f32_e32 v27, v114, v150
	v_fmac_f32_e32 v20, v114, v154
	v_fmac_f32_e32 v21, v114, v158
	v_fmac_f32_e32 v22, v115, v131
	v_fmac_f32_e32 v23, v115, v135
	v_fmac_f32_e32 v24, v115, v139
	v_fmac_f32_e32 v25, v115, v143
	v_fmac_f32_e32 v26, v115, v147
	v_fmac_f32_e32 v27, v115, v151
	v_fmac_f32_e32 v20, v115, v155
	v_fmac_f32_e32 v21, v115, v159
	s_waitcnt lgkmcnt(4)
	ds_read_b128 v[128:131], v4 offset:224
	ds_read_b128 v[132:135], v4 offset:4320
	ds_read_b128 v[136:139], v4 offset:8416
	ds_read_b128 v[140:143], v4 offset:12512
	ds_read_b128 v[144:147], v4 offset:16608
	ds_read_b128 v[148:151], v4 offset:20704
	ds_read_b128 v[152:155], v4 offset:24800
	ds_read_b128 v[156:159], v4 offset:28896
	s_waitcnt lgkmcnt(8)
	v_fmac_f32_e32 v22, v116, v160
	v_fmac_f32_e32 v23, v116, v164
	v_fmac_f32_e32 v24, v116, v168
	v_fmac_f32_e32 v25, v116, v172
	v_fmac_f32_e32 v26, v116, v176
	v_fmac_f32_e32 v27, v116, v180
	v_fmac_f32_e32 v20, v116, v184
	v_fmac_f32_e32 v21, v116, v188
	v_fmac_f32_e32 v22, v117, v161
	v_fmac_f32_e32 v23, v117, v165
	v_fmac_f32_e32 v24, v117, v169
	v_fmac_f32_e32 v25, v117, v173
	v_fmac_f32_e32 v26, v117, v177
	v_fmac_f32_e32 v27, v117, v181
	v_fmac_f32_e32 v20, v117, v185
	v_fmac_f32_e32 v21, v117, v189
	v_fmac_f32_e32 v22, v118, v162
	v_fmac_f32_e32 v23, v118, v166
	v_fmac_f32_e32 v24, v118, v170
	v_fmac_f32_e32 v25, v118, v174
	v_fmac_f32_e32 v26, v118, v178
	v_fmac_f32_e32 v27, v118, v182
	v_fmac_f32_e32 v20, v118, v186
	v_fmac_f32_e32 v21, v118, v190
	v_fmac_f32_e32 v22, v119, v163
	v_fmac_f32_e32 v23, v119, v167
	v_fmac_f32_e32 v24, v119, v171
	v_fmac_f32_e32 v25, v119, v175
	v_fmac_f32_e32 v26, v119, v179
	v_fmac_f32_e32 v27, v119, v183
	v_fmac_f32_e32 v20, v119, v187
	v_fmac_f32_e32 v21, v119, v191
	s_waitcnt lgkmcnt(4)
	ds_read_b128 v[160:163], v4 offset:240
	ds_read_b128 v[164:167], v4 offset:4336
	ds_read_b128 v[168:171], v4 offset:8432
	ds_read_b128 v[172:175], v4 offset:12528
	ds_read_b128 v[176:179], v4 offset:16624
	ds_read_b128 v[180:183], v4 offset:20720
	ds_read_b128 v[184:187], v4 offset:24816
	ds_read_b128 v[188:191], v4 offset:28912
	s_waitcnt lgkmcnt(8)
	v_fmac_f32_e32 v22, v120, v128
	v_fmac_f32_e32 v23, v120, v132
	v_fmac_f32_e32 v24, v120, v136
	v_fmac_f32_e32 v25, v120, v140
	v_fmac_f32_e32 v26, v120, v144
	v_fmac_f32_e32 v27, v120, v148
	v_fmac_f32_e32 v20, v120, v152
	v_fmac_f32_e32 v21, v120, v156
	v_fmac_f32_e32 v22, v121, v129
	v_fmac_f32_e32 v23, v121, v133
	v_fmac_f32_e32 v24, v121, v137
	v_fmac_f32_e32 v25, v121, v141
	v_fmac_f32_e32 v26, v121, v145
	v_fmac_f32_e32 v27, v121, v149
	v_fmac_f32_e32 v20, v121, v153
	v_fmac_f32_e32 v21, v121, v157
	v_fmac_f32_e32 v22, v122, v130
	v_fmac_f32_e32 v23, v122, v134
	v_fmac_f32_e32 v24, v122, v138
	v_fmac_f32_e32 v25, v122, v142
	v_fmac_f32_e32 v26, v122, v146
	v_fmac_f32_e32 v27, v122, v150
	v_fmac_f32_e32 v20, v122, v154
	v_fmac_f32_e32 v21, v122, v158
	v_fmac_f32_e32 v22, v123, v131
	v_fmac_f32_e32 v23, v123, v135
	v_fmac_f32_e32 v24, v123, v139
	v_fmac_f32_e32 v25, v123, v143
	v_fmac_f32_e32 v26, v123, v147
	v_fmac_f32_e32 v27, v123, v151
	v_fmac_f32_e32 v20, v123, v155
	v_fmac_f32_e32 v21, v123, v159
	s_waitcnt lgkmcnt(0)
	v_fmac_f32_e32 v22, v124, v160
	v_fmac_f32_e32 v23, v124, v164
	v_fmac_f32_e32 v24, v124, v168
	v_fmac_f32_e32 v25, v124, v172
	v_fmac_f32_e32 v26, v124, v176
	v_fmac_f32_e32 v27, v124, v180
	v_fmac_f32_e32 v20, v124, v184
	v_fmac_f32_e32 v21, v124, v188
	v_fmac_f32_e32 v22, v125, v161
	v_fmac_f32_e32 v23, v125, v165
	v_fmac_f32_e32 v24, v125, v169
	v_fmac_f32_e32 v25, v125, v173
	v_fmac_f32_e32 v26, v125, v177
	v_fmac_f32_e32 v27, v125, v181
	v_fmac_f32_e32 v20, v125, v185
	v_fmac_f32_e32 v21, v125, v189
	v_fmac_f32_e32 v22, v126, v162
	v_fmac_f32_e32 v23, v126, v166
	v_fmac_f32_e32 v24, v126, v170
	v_fmac_f32_e32 v25, v126, v174
	v_fmac_f32_e32 v26, v126, v178
	v_fmac_f32_e32 v27, v126, v182
	v_fmac_f32_e32 v20, v126, v186
	v_fmac_f32_e32 v21, v126, v190
	v_fmac_f32_e32 v22, v127, v163
	v_fmac_f32_e32 v23, v127, v167
	v_fmac_f32_e32 v24, v127, v171
	v_fmac_f32_e32 v25, v127, v175
	v_fmac_f32_e32 v26, v127, v179
	v_fmac_f32_e32 v27, v127, v183
	v_fmac_f32_e32 v20, v127, v187
	v_fmac_f32_e32 v21, v127, v191
	s_cmp_eq_u32 vcc_lo, 1
	s_cbranch_scc1 .Lpm_done
	global_load_dword v96, v[2:3], off
	v_lshl_add_u64 v[2:3], v[2:3], 0, s[6:7]
	global_load_dword v97, v[2:3], off
	v_lshl_add_u64 v[2:3], v[2:3], 0, s[6:7]
	global_load_dword v98, v[2:3], off
	v_lshl_add_u64 v[2:3], v[2:3], 0, s[6:7]
	global_load_dword v99, v[2:3], off
	v_lshl_add_u64 v[2:3], v[2:3], 0, s[6:7]
	global_load_dword v100, v[2:3], off
	v_lshl_add_u64 v[2:3], v[2:3], 0, s[6:7]
	global_load_dword v101, v[2:3], off
	v_lshl_add_u64 v[2:3], v[2:3], 0, s[6:7]
	global_load_dword v102, v[2:3], off
	v_lshl_add_u64 v[2:3], v[2:3], 0, s[6:7]
	global_load_dword v103, v[2:3], off
	v_lshl_add_u64 v[2:3], v[2:3], 0, s[6:7]
	global_load_dword v104, v[2:3], off
	v_lshl_add_u64 v[2:3], v[2:3], 0, s[6:7]
	global_load_dword v105, v[2:3], off
	v_lshl_add_u64 v[2:3], v[2:3], 0, s[6:7]
	global_load_dword v106, v[2:3], off
	v_lshl_add_u64 v[2:3], v[2:3], 0, s[6:7]
	global_load_dword v107, v[2:3], off
	v_lshl_add_u64 v[2:3], v[2:3], 0, s[6:7]
	global_load_dword v108, v[2:3], off
	v_lshl_add_u64 v[2:3], v[2:3], 0, s[6:7]
	global_load_dword v109, v[2:3], off
	v_lshl_add_u64 v[2:3], v[2:3], 0, s[6:7]
	global_load_dword v110, v[2:3], off
	v_lshl_add_u64 v[2:3], v[2:3], 0, s[6:7]
	global_load_dword v111, v[2:3], off
	v_lshl_add_u64 v[2:3], v[2:3], 0, s[6:7]
	v_add_u32_e32 v4, 0x100, v4
	s_add_i32 vcc_lo, vcc_lo, -1
	s_branch .Lpm_loop
; __device__ __forceinline__ void prep_mod_job(const Params& p, int m, float* sm) {
;     ...
; #pragma unroll
;   for (int s = 0; s < 8; ++s) red[(kq * 8 + s) * 64 + col] = acc[s];
;   __syncthreads();
; #pragma unroll
;   for (int i = 0; i < 2; ++i) {
;     int o = tid + i * 256;
;     int s = o >> 6, c = o & 63;
;     float v = red[(0 * 8 + s) * 64 + c] + red[(1 * 8 + s) * 64 + c] + red[(2 * 8 + s) * 64 + c] + red[(3 * 8 + s) * 64 + c];
;     v += p.ada_b[l * 9216 + col0 + c];
;     p.mod[(size_t)(l * 40 + sg * 8 + s) * 9216 + col0 + c] = v;
;   }
.Lpm_done:
	v_lshlrev_b32_e32 v14, 2, v16
	v_add_u32_e32 v4, s65, v14
	s_mul_i32 s6, s10, 0x2400
	v_lshl_add_u32 v2, v37, 11, v4
	s_add_i32 s6, s4, s6
	ds_write2st64_b32 v2, v22, v23 offset0:128 offset1:129
	ds_write2st64_b32 v2, v24, v25 offset0:130 offset1:131
	ds_write2st64_b32 v2, v26, v27 offset0:132 offset1:133
	ds_write2st64_b32 v2, v20, v21 offset0:134 offset1:135
	v_or_b32_e32 v2, s6, v16
	v_ashrrev_i32_e32 v3, 31, v2
	v_lshl_add_u64 v[2:3], v[2:3], 2, s[18:19]
	s_waitcnt lgkmcnt(0)
	s_barrier
	global_load_dword v12, v[2:3], off
	v_add_u32_e32 v13, 0x100, v35
	v_and_b32_e32 v5, 0x3fffffc0, v35
	v_and_b32_e32 v6, 0x3fffffc0, v13
	v_lshl_add_u32 v8, v5, 2, v4
	v_lshl_add_u32 v16, v6, 2, v4
	ds_read2st64_b32 v[4:5], v36 offset0:128 offset1:132
	ds_read2st64_b32 v[6:7], v8 offset0:136 offset1:144
	ds_read_b32 v18, v8 offset:38912
	ds_read_b32 v19, v16 offset:38912
	s_mul_i32 s10, s10, 40
	s_lshl_b32 s6, s11, 3
	s_lshl_b64 s[4:5], s[4:5], 2
	s_add_i32 s6, s6, s10
	s_add_u32 s4, s22, s4
	s_waitcnt lgkmcnt(2)
	v_add_f32_e32 v4, v4, v6
	s_addc_u32 s5, s23, s5
	v_add_f32_e32 v4, v4, v7
	v_add_u32_e32 v10, s6, v37
	v_lshl_add_u64 v[8:9], s[4:5], 0, v[14:15]
	s_waitcnt lgkmcnt(1)
	v_add_f32_e32 v4, v4, v18
	v_mad_i64_i32 v[10:11], s[4:5], v10, s87, v[8:9]
	v_ashrrev_i32_e32 v6, 6, v13
	v_add_u32_e32 v6, s6, v6
	v_mad_i64_i32 v[6:7], s[4:5], v6, s87, v[8:9]
	s_waitcnt vmcnt(0)
	v_add_f32_e32 v4, v4, v12
	global_store_dword v[10:11], v4, off
	global_load_dword v4, v[2:3], off
	ds_read2st64_b32 v[2:3], v16 offset0:136 offset1:144
	s_waitcnt lgkmcnt(0)
	v_add_f32_e32 v2, v5, v2
	v_add_f32_e32 v2, v2, v3
	v_add_f32_e32 v2, v2, v19
	s_waitcnt vmcnt(0)
	v_add_f32_e32 v2, v2, v4
	global_store_dword v[6:7], v2, off
	s_barrier
	s_branch .LBB0_13

; __device__ __forceinline__ void prep_sw_job(const Params& p, int job, float* sm) {
;     ...
;   int col = tid & 63, kq = tid >> 6;
;   float acc[8];
; #pragma unroll
;   for (int q = 0; q < 8; ++q) acc[q] = 0.f;
;   const float* wp = W + (size_t)(kq * 256) * ldw + col0 + col;
;   const float* scp = sc + kq * 256;
; #pragma unroll 8
;   for (int k = 0; k < 256; ++k) {
;     float w = wp[(size_t)k * ldw];
.LBB0_761:
	s_or_b64 exec, exec, s[34:35]
	v_ashrrev_i32_e32 v1, 6, v0
	v_lshlrev_b32_e32 v2, 8, v1
	v_mad_i64_i32 v[2:3], s[34:35], s30, v2, 0
	v_and_b32_e32 v12, 63, v0
	v_lshl_add_u64 v[2:3], v[2:3], 2, s[28:29]
	s_ashr_i32 s17, s16, 31
	v_lshl_add_u64 v[2:3], s[16:17], 2, v[2:3]
	v_lshlrev_b32_e32 v198, 2, v12
	v_mov_b32_e32 v4, 0
	v_lshl_add_u64 v[2:3], v[2:3], 0, v[198:199]
	v_lshl_add_u32 v13, v1, 10, s65
	s_lshl_b32 s66, s30, 5
	s_lshl_b32 s28, s30, 2
	s_mov_b32 s29, s67
	s_mov_b32 s17, 0
	v_mov_b32_e32 v5, v4
	v_mov_b32_e32 v10, v4
	v_mov_b32_e32 v11, v4
	v_mov_b32_e32 v8, v4
	v_mov_b32_e32 v9, v4
	v_mov_b32_e32 v6, v4
	v_mov_b32_e32 v7, v4
	s_waitcnt vmcnt(0) lgkmcnt(0)
	s_barrier
	v_mov_b32_e32 v54, v13
	global_load_dword v64, v[2:3], off
	v_lshl_add_u64 v[2:3], v[2:3], 0, s[28:29]
	global_load_dword v65, v[2:3], off
	v_lshl_add_u64 v[2:3], v[2:3], 0, s[28:29]
	global_load_dword v66, v[2:3], off
	v_lshl_add_u64 v[2:3], v[2:3], 0, s[28:29]
	global_load_dword v67, v[2:3], off
	v_lshl_add_u64 v[2:3], v[2:3], 0, s[28:29]
	global_load_dword v68, v[2:3], off
	v_lshl_add_u64 v[2:3], v[2:3], 0, s[28:29]
	global_load_dword v69, v[2:3], off
	v_lshl_add_u64 v[2:3], v[2:3], 0, s[28:29]
	global_load_dword v70, v[2:3], off
	v_lshl_add_u64 v[2:3], v[2:3], 0, s[28:29]
	global_load_dword v71, v[2:3], off
	v_lshl_add_u64 v[2:3], v[2:3], 0, s[28:29]
	global_load_dword v72, v[2:3], off
	v_lshl_add_u64 v[2:3], v[2:3], 0, s[28:29]
	global_load_dword v73, v[2:3], off
	v_lshl_add_u64 v[2:3], v[2:3], 0, s[28:29]
	global_load_dword v74, v[2:3], off
	v_lshl_add_u64 v[2:3], v[2:3], 0, s[28:29]
	global_load_dword v75, v[2:3], off
	v_lshl_add_u64 v[2:3], v[2:3], 0, s[28:29]
	global_load_dword v76, v[2:3], off
	v_lshl_add_u64 v[2:3], v[2:3], 0, s[28:29]
	global_load_dword v77, v[2:3], off
	v_lshl_add_u64 v[2:3], v[2:3], 0, s[28:29]
	global_load_dword v78, v[2:3], off
	v_lshl_add_u64 v[2:3], v[2:3], 0, s[28:29]
	global_load_dword v79, v[2:3], off
	v_lshl_add_u64 v[2:3], v[2:3], 0, s[28:29]
	global_load_dword v80, v[2:3], off
	v_lshl_add_u64 v[2:3], v[2:3], 0, s[28:29]
	global_load_dword v81, v[2:3], off
	v_lshl_add_u64 v[2:3], v[2:3], 0, s[28:29]
	global_load_dword v82, v[2:3], off
	v_lshl_add_u64 v[2:3], v[2:3], 0, s[28:29]
	global_load_dword v83, v[2:3], off
	v_lshl_add_u64 v[2:3], v[2:3], 0, s[28:29]
	global_load_dword v84, v[2:3], off
	v_lshl_add_u64 v[2:3], v[2:3], 0, s[28:29]
	global_load_dword v85, v[2:3], off
	v_lshl_add_u64 v[2:3], v[2:3], 0, s[28:29]
	global_load_dword v86, v[2:3], off
	v_lshl_add_u64 v[2:3], v[2:3], 0, s[28:29]
	global_load_dword v87, v[2:3], off
	v_lshl_add_u64 v[2:3], v[2:3], 0, s[28:29]
	global_load_dword v88, v[2:3], off
	v_lshl_add_u64 v[2:3], v[2:3], 0, s[28:29]
	global_load_dword v89, v[2:3], off
	v_lshl_add_u64 v[2:3], v[2:3], 0, s[28:29]
	global_load_dword v90, v[2:3], off
	v_lshl_add_u64 v[2:3], v[2:3], 0, s[28:29]
	global_load_dword v91, v[2:3], off
	v_lshl_add_u64 v[2:3], v[2:3], 0, s[28:29]
	global_load_dword v92, v[2:3], off
	v_lshl_add_u64 v[2:3], v[2:3], 0, s[28:29]
	global_load_dword v93, v[2:3], off
	v_lshl_add_u64 v[2:3], v[2:3], 0, s[28:29]
	global_load_dword v94, v[2:3], off
	v_lshl_add_u64 v[2:3], v[2:3], 0, s[28:29]
	global_load_dword v95, v[2:3], off
	v_lshl_add_u64 v[2:3], v[2:3], 0, s[28:29]
	global_load_dword v96, v[2:3], off
	v_lshl_add_u64 v[2:3], v[2:3], 0, s[28:29]
	global_load_dword v97, v[2:3], off
	v_lshl_add_u64 v[2:3], v[2:3], 0, s[28:29]
	global_load_dword v98, v[2:3], off
	v_lshl_add_u64 v[2:3], v[2:3], 0, s[28:29]
	global_load_dword v99, v[2:3], off
	v_lshl_add_u64 v[2:3], v[2:3], 0, s[28:29]
	global_load_dword v100, v[2:3], off
	v_lshl_add_u64 v[2:3], v[2:3], 0, s[28:29]
	global_load_dword v101, v[2:3], off
	v_lshl_add_u64 v[2:3], v[2:3], 0, s[28:29]
	global_load_dword v102, v[2:3], off
	v_lshl_add_u64 v[2:3], v[2:3], 0, s[28:29]
	global_load_dword v103, v[2:3], off
	v_lshl_add_u64 v[2:3], v[2:3], 0, s[28:29]
	global_load_dword v104, v[2:3], off
	v_lshl_add_u64 v[2:3], v[2:3], 0, s[28:29]
	global_load_dword v105, v[2:3], off
	v_lshl_add_u64 v[2:3], v[2:3], 0, s[28:29]
	global_load_dword v106, v[2:3], off
	v_lshl_add_u64 v[2:3], v[2:3], 0, s[28:29]
	global_load_dword v107, v[2:3], off
	v_lshl_add_u64 v[2:3], v[2:3], 0, s[28:29]
	global_load_dword v108, v[2:3], off
	v_lshl_add_u64 v[2:3], v[2:3], 0, s[28:29]
	global_load_dword v109, v[2:3], off
	v_lshl_add_u64 v[2:3], v[2:3], 0, s[28:29]
	global_load_dword v110, v[2:3], off
	v_lshl_add_u64 v[2:3], v[2:3], 0, s[28:29]
	global_load_dword v111, v[2:3], off
	v_lshl_add_u64 v[2:3], v[2:3], 0, s[28:29]
	s_mov_b32 s17, 4
; __device__ __forceinline__ void prep_sw_job(const Params& p, int job, float* sm) {
;     ...
; #pragma unroll 8
;   for (int k = 0; k < 256; ++k) {
;     float w = wp[(size_t)k * ldw];
; #pragma unroll
;     for (int q = 0; q < 8; ++q) acc[q] += scp[q * 1024 + k] * w;
;   }
.Lsw_loop:
	s_waitcnt vmcnt(32)
	ds_read_b128 v[16:19], v54 offset:0
	ds_read_b128 v[20:23], v54 offset:4096
	ds_read_b128 v[24:27], v54 offset:8192
	ds_read_b128 v[28:31], v54 offset:12288
	ds_read_b128 v[32:35], v54 offset:16384
	ds_read_b128 v[36:39], v54 offset:20480
	ds_read_b128 v[40:43], v54 offset:24576
	ds_read_b128 v[44:47], v54 offset:28672
	s_waitcnt lgkmcnt(4)
	ds_read_b128 v[128:131], v54 offset:16
	ds_read_b128 v[132:135], v54 offset:4112
	ds_read_b128 v[136:139], v54 offset:8208
	ds_read_b128 v[140:143], v54 offset:12304
	ds_read_b128 v[144:147], v54 offset:16400
	ds_read_b128 v[148:151], v54 offset:20496
	ds_read_b128 v[152:155], v54 offset:24592
	ds_read_b128 v[156:159], v54 offset:28688
	s_waitcnt lgkmcnt(8)
	v_fmac_f32_e32 v10, v64, v16
	v_fmac_f32_e32 v11, v64, v20
	v_fmac_f32_e32 v8, v64, v24
	v_fmac_f32_e32 v9, v64, v28
	v_fmac_f32_e32 v6, v64, v32
	v_fmac_f32_e32 v7, v64, v36
	v_fmac_f32_e32 v4, v64, v40
	v_fmac_f32_e32 v5, v64, v44
	v_fmac_f32_e32 v10, v65, v17
	v_fmac_f32_e32 v11, v65, v21
	v_fmac_f32_e32 v8, v65, v25
	v_fmac_f32_e32 v9, v65, v29
	v_fmac_f32_e32 v6, v65, v33
	v_fmac_f32_e32 v7, v65, v37
	v_fmac_f32_e32 v4, v65, v41
	v_fmac_f32_e32 v5, v65, v45
	v_fmac_f32_e32 v10, v66, v18
	v_fmac_f32_e32 v11, v66, v22
	v_fmac_f32_e32 v8, v66, v26
	v_fmac_f32_e32 v9, v66, v30
	v_fmac_f32_e32 v6, v66, v34
	v_fmac_f32_e32 v7, v66, v38
	v_fmac_f32_e32 v4, v66, v42
	v_fmac_f32_e32 v5, v66, v46
	v_fmac_f32_e32 v10, v67, v19
	v_fmac_f32_e32 v11, v67, v23
	v_fmac_f32_e32 v8, v67, v27
	v_fmac_f32_e32 v9, v67, v31
	v_fmac_f32_e32 v6, v67, v35
	v_fmac_f32_e32 v7, v67, v39
	v_fmac_f32_e32 v4, v67, v43
	v_fmac_f32_e32 v5, v67, v47
	s_waitcnt lgkmcnt(4)
	ds_read_b128 v[16:19], v54 offset:32
	ds_read_b128 v[20:23], v54 offset:4128
	ds_read_b128 v[24:27], v54 offset:8224
	ds_read_b128 v[28:31], v54 offset:12320
	ds_read_b128 v[32:35], v54 offset:16416
	ds_read_b128 v[36:39], v54 offset:20512
	ds_read_b128 v[40:43], v54 offset:24608
	ds_read_b128 v[44:47], v54 offset:28704
	s_waitcnt lgkmcnt(8)
	v_fmac_f32_e32 v10, v68, v128
	v_fmac_f32_e32 v11, v68, v132
	v_fmac_f32_e32 v8, v68, v136
	v_fmac_f32_e32 v9, v68, v140
	v_fmac_f32_e32 v6, v68, v144
	v_fmac_f32_e32 v7, v68, v148
	v_fmac_f32_e32 v4, v68, v152
	v_fmac_f32_e32 v5, v68, v156
	v_fmac_f32_e32 v10, v69, v129
	v_fmac_f32_e32 v11, v69, v133
	v_fmac_f32_e32 v8, v69, v137
	v_fmac_f32_e32 v9, v69, v141
	v_fmac_f32_e32 v6, v69, v145
	v_fmac_f32_e32 v7, v69, v149
	v_fmac_f32_e32 v4, v69, v153
	v_fmac_f32_e32 v5, v69, v157
	v_fmac_f32_e32 v10, v70, v130
	v_fmac_f32_e32 v11, v70, v134
	v_fmac_f32_e32 v8, v70, v138
	v_fmac_f32_e32 v9, v70, v142
	v_fmac_f32_e32 v6, v70, v146
	v_fmac_f32_e32 v7, v70, v150
	v_fmac_f32_e32 v4, v70, v154
	v_fmac_f32_e32 v5, v70, v158
	v_fmac_f32_e32 v10, v71, v131
	v_fmac_f32_e32 v11, v71, v135
	v_fmac_f32_e32 v8, v71, v139
	v_fmac_f32_e32 v9, v71, v143
	v_fmac_f32_e32 v6, v71, v147
	v_fmac_f32_e32 v7, v71, v151
	v_fmac_f32_e32 v4, v71, v155
	v_fmac_f32_e32 v5, v71, v159
	s_waitcnt lgkmcnt(4)
	ds_read_b128 v[128:131], v54 offset:48
	ds_read_b128 v[132:135], v54 offset:4144
	ds_read_b128 v[136:139], v54 offset:8240
	ds_read_b128 v[140:143], v54 offset:12336
	ds_read_b128 v[144:147], v54 offset:16432
	ds_read_b128 v[148:151], v54 offset:20528
	ds_read_b128 v[152:155], v54 offset:24624
	ds_read_b128 v[156:159], v54 offset:28720
	s_waitcnt lgkmcnt(8)
	v_fmac_f32_e32 v10, v72, v16
	v_fmac_f32_e32 v11, v72, v20
	v_fmac_f32_e32 v8, v72, v24
	v_fmac_f32_e32 v9, v72, v28
	v_fmac_f32_e32 v6, v72, v32
	v_fmac_f32_e32 v7, v72, v36
	v_fmac_f32_e32 v4, v72, v40
	v_fmac_f32_e32 v5, v72, v44
	v_fmac_f32_e32 v10, v73, v17
	v_fmac_f32_e32 v11, v73, v21
	v_fmac_f32_e32 v8, v73, v25
	v_fmac_f32_e32 v9, v73, v29
	v_fmac_f32_e32 v6, v73, v33
	v_fmac_f32_e32 v7, v73, v37
	v_fmac_f32_e32 v4, v73, v41
	v_fmac_f32_e32 v5, v73, v45
	v_fmac_f32_e32 v10, v74, v18
	v_fmac_f32_e32 v11, v74, v22
	v_fmac_f32_e32 v8, v74, v26
	v_fmac_f32_e32 v9, v74, v30
	v_fmac_f32_e32 v6, v74, v34
	v_fmac_f32_e32 v7, v74, v38
	v_fmac_f32_e32 v4, v74, v42
	v_fmac_f32_e32 v5, v74, v46
	v_fmac_f32_e32 v10, v75, v19
	v_fmac_f32_e32 v11, v75, v23
	v_fmac_f32_e32 v8, v75, v27
	v_fmac_f32_e32 v9, v75, v31
	v_fmac_f32_e32 v6, v75, v35
	v_fmac_f32_e32 v7, v75, v39
	v_fmac_f32_e32 v4, v75, v43
	v_fmac_f32_e32 v5, v75, v47
	s_waitcnt lgkmcnt(0)
	v_fmac_f32_e32 v10, v76, v128
	v_fmac_f32_e32 v11, v76, v132
	v_fmac_f32_e32 v8, v76, v136
	v_fmac_f32_e32 v9, v76, v140
	v_fmac_f32_e32 v6, v76, v144
	v_fmac_f32_e32 v7, v76, v148
	v_fmac_f32_e32 v4, v76, v152
	v_fmac_f32_e32 v5, v76, v156
	v_fmac_f32_e32 v10, v77, v129
	v_fmac_f32_e32 v11, v77, v133
	v_fmac_f32_e32 v8, v77, v137
	v_fmac_f32_e32 v9, v77, v141
	v_fmac_f32_e32 v6, v77, v145
	v_fmac_f32_e32 v7, v77, v149
	v_fmac_f32_e32 v4, v77, v153
	v_fmac_f32_e32 v5, v77, v157
	v_fmac_f32_e32 v10, v78, v130
	v_fmac_f32_e32 v11, v78, v134
	v_fmac_f32_e32 v8, v78, v138
	v_fmac_f32_e32 v9, v78, v142
	v_fmac_f32_e32 v6, v78, v146
	v_fmac_f32_e32 v7, v78, v150
	v_fmac_f32_e32 v4, v78, v154
	v_fmac_f32_e32 v5, v78, v158
	v_fmac_f32_e32 v10, v79, v131
	v_fmac_f32_e32 v11, v79, v135
	v_fmac_f32_e32 v8, v79, v139
	v_fmac_f32_e32 v9, v79, v143
	v_fmac_f32_e32 v6, v79, v147
	v_fmac_f32_e32 v7, v79, v151
	v_fmac_f32_e32 v4, v79, v155
	v_fmac_f32_e32 v5, v79, v159
	global_load_dword v112, v[2:3], off
	v_lshl_add_u64 v[2:3], v[2:3], 0, s[28:29]
	global_load_dword v113, v[2:3], off
	v_lshl_add_u64 v[2:3], v[2:3], 0, s[28:29]
	global_load_dword v114, v[2:3], off
	v_lshl_add_u64 v[2:3], v[2:3], 0, s[28:29]
	global_load_dword v115, v[2:3], off
	v_lshl_add_u64 v[2:3], v[2:3], 0, s[28:29]
	global_load_dword v116, v[2:3], off
	v_lshl_add_u64 v[2:3], v[2:3], 0, s[28:29]
	global_load_dword v117, v[2:3], off
	v_lshl_add_u64 v[2:3], v[2:3], 0, s[28:29]
	global_load_dword v118, v[2:3], off
	v_lshl_add_u64 v[2:3], v[2:3], 0, s[28:29]
	global_load_dword v119, v[2:3], off
	v_lshl_add_u64 v[2:3], v[2:3], 0, s[28:29]
	global_load_dword v120, v[2:3], off
	v_lshl_add_u64 v[2:3], v[2:3], 0, s[28:29]
	global_load_dword v121, v[2:3], off
	v_lshl_add_u64 v[2:3], v[2:3], 0, s[28:29]
	global_load_dword v122, v[2:3], off
	v_lshl_add_u64 v[2:3], v[2:3], 0, s[28:29]
	global_load_dword v123, v[2:3], off
	v_lshl_add_u64 v[2:3], v[2:3], 0, s[28:29]
	global_load_dword v124, v[2:3], off
	v_lshl_add_u64 v[2:3], v[2:3], 0, s[28:29]
	global_load_dword v125, v[2:3], off
	v_lshl_add_u64 v[2:3], v[2:3], 0, s[28:29]
	global_load_dword v126, v[2:3], off
	v_lshl_add_u64 v[2:3], v[2:3], 0, s[28:29]
	global_load_dword v127, v[2:3], off
	v_lshl_add_u64 v[2:3], v[2:3], 0, s[28:29]
	s_waitcnt vmcnt(32)
; __device__ __forceinline__ void prep_sw_job(const Params& p, int job, float* sm) {
;     ...
; #pragma unroll 8
;   for (int k = 0; k < 256; ++k) {
;     float w = wp[(size_t)k * ldw];
; #pragma unroll
;     for (int q = 0; q < 8; ++q) acc[q] += scp[q * 1024 + k] * w;
;   }
	ds_read_b128 v[16:19], v54 offset:64
	ds_read_b128 v[20:23], v54 offset:4160
	ds_read_b128 v[24:27], v54 offset:8256
	ds_read_b128 v[28:31], v54 offset:12352
	ds_read_b128 v[32:35], v54 offset:16448
	ds_read_b128 v[36:39], v54 offset:20544
	ds_read_b128 v[40:43], v54 offset:24640
	ds_read_b128 v[44:47], v54 offset:28736
	s_waitcnt lgkmcnt(4)
	ds_read_b128 v[128:131], v54 offset:80
	ds_read_b128 v[132:135], v54 offset:4176
	ds_read_b128 v[136:139], v54 offset:8272
	ds_read_b128 v[140:143], v54 offset:12368
	ds_read_b128 v[144:147], v54 offset:16464
	ds_read_b128 v[148:151], v54 offset:20560
	ds_read_b128 v[152:155], v54 offset:24656
	ds_read_b128 v[156:159], v54 offset:28752
	s_waitcnt lgkmcnt(8)
	v_fmac_f32_e32 v10, v80, v16
	v_fmac_f32_e32 v11, v80, v20
	v_fmac_f32_e32 v8, v80, v24
	v_fmac_f32_e32 v9, v80, v28
	v_fmac_f32_e32 v6, v80, v32
	v_fmac_f32_e32 v7, v80, v36
	v_fmac_f32_e32 v4, v80, v40
	v_fmac_f32_e32 v5, v80, v44
	v_fmac_f32_e32 v10, v81, v17
	v_fmac_f32_e32 v11, v81, v21
	v_fmac_f32_e32 v8, v81, v25
	v_fmac_f32_e32 v9, v81, v29
	v_fmac_f32_e32 v6, v81, v33
	v_fmac_f32_e32 v7, v81, v37
	v_fmac_f32_e32 v4, v81, v41
	v_fmac_f32_e32 v5, v81, v45
	v_fmac_f32_e32 v10, v82, v18
	v_fmac_f32_e32 v11, v82, v22
	v_fmac_f32_e32 v8, v82, v26
	v_fmac_f32_e32 v9, v82, v30
	v_fmac_f32_e32 v6, v82, v34
	v_fmac_f32_e32 v7, v82, v38
	v_fmac_f32_e32 v4, v82, v42
	v_fmac_f32_e32 v5, v82, v46
	v_fmac_f32_e32 v10, v83, v19
	v_fmac_f32_e32 v11, v83, v23
	v_fmac_f32_e32 v8, v83, v27
	v_fmac_f32_e32 v9, v83, v31
	v_fmac_f32_e32 v6, v83, v35
	v_fmac_f32_e32 v7, v83, v39
	v_fmac_f32_e32 v4, v83, v43
	v_fmac_f32_e32 v5, v83, v47
	s_waitcnt lgkmcnt(4)
	ds_read_b128 v[16:19], v54 offset:96
	ds_read_b128 v[20:23], v54 offset:4192
	ds_read_b128 v[24:27], v54 offset:8288
	ds_read_b128 v[28:31], v54 offset:12384
	ds_read_b128 v[32:35], v54 offset:16480
	ds_read_b128 v[36:39], v54 offset:20576
	ds_read_b128 v[40:43], v54 offset:24672
	ds_read_b128 v[44:47], v54 offset:28768
	s_waitcnt lgkmcnt(8)
	v_fmac_f32_e32 v10, v84, v128
	v_fmac_f32_e32 v11, v84, v132
	v_fmac_f32_e32 v8, v84, v136
	v_fmac_f32_e32 v9, v84, v140
	v_fmac_f32_e32 v6, v84, v144
	v_fmac_f32_e32 v7, v84, v148
	v_fmac_f32_e32 v4, v84, v152
	v_fmac_f32_e32 v5, v84, v156
	v_fmac_f32_e32 v10, v85, v129
	v_fmac_f32_e32 v11, v85, v133
	v_fmac_f32_e32 v8, v85, v137
	v_fmac_f32_e32 v9, v85, v141
	v_fmac_f32_e32 v6, v85, v145
	v_fmac_f32_e32 v7, v85, v149
	v_fmac_f32_e32 v4, v85, v153
	v_fmac_f32_e32 v5, v85, v157
	v_fmac_f32_e32 v10, v86, v130
	v_fmac_f32_e32 v11, v86, v134
	v_fmac_f32_e32 v8, v86, v138
	v_fmac_f32_e32 v9, v86, v142
	v_fmac_f32_e32 v6, v86, v146
	v_fmac_f32_e32 v7, v86, v150
	v_fmac_f32_e32 v4, v86, v154
	v_fmac_f32_e32 v5, v86, v158
	v_fmac_f32_e32 v10, v87, v131
	v_fmac_f32_e32 v11, v87, v135
	v_fmac_f32_e32 v8, v87, v139
	v_fmac_f32_e32 v9, v87, v143
	v_fmac_f32_e32 v6, v87, v147
	v_fmac_f32_e32 v7, v87, v151
	v_fmac_f32_e32 v4, v87, v155
	v_fmac_f32_e32 v5, v87, v159
	s_waitcnt lgkmcnt(4)
	ds_read_b128 v[128:131], v54 offset:112
	ds_read_b128 v[132:135], v54 offset:4208
	ds_read_b128 v[136:139], v54 offset:8304
	ds_read_b128 v[140:143], v54 offset:12400
	ds_read_b128 v[144:147], v54 offset:16496
	ds_read_b128 v[148:151], v54 offset:20592
	ds_read_b128 v[152:155], v54 offset:24688
	ds_read_b128 v[156:159], v54 offset:28784
	s_waitcnt lgkmcnt(8)
	v_fmac_f32_e32 v10, v88, v16
	v_fmac_f32_e32 v11, v88, v20
	v_fmac_f32_e32 v8, v88, v24
	v_fmac_f32_e32 v9, v88, v28
	v_fmac_f32_e32 v6, v88, v32
	v_fmac_f32_e32 v7, v88, v36
	v_fmac_f32_e32 v4, v88, v40
	v_fmac_f32_e32 v5, v88, v44
	v_fmac_f32_e32 v10, v89, v17
	v_fmac_f32_e32 v11, v89, v21
	v_fmac_f32_e32 v8, v89, v25
	v_fmac_f32_e32 v9, v89, v29
	v_fmac_f32_e32 v6, v89, v33
	v_fmac_f32_e32 v7, v89, v37
	v_fmac_f32_e32 v4, v89, v41
	v_fmac_f32_e32 v5, v89, v45
	v_fmac_f32_e32 v10, v90, v18
	v_fmac_f32_e32 v11, v90, v22
	v_fmac_f32_e32 v8, v90, v26
	v_fmac_f32_e32 v9, v90, v30
	v_fmac_f32_e32 v6, v90, v34
	v_fmac_f32_e32 v7, v90, v38
	v_fmac_f32_e32 v4, v90, v42
	v_fmac_f32_e32 v5, v90, v46
	v_fmac_f32_e32 v10, v91, v19
	v_fmac_f32_e32 v11, v91, v23
	v_fmac_f32_e32 v8, v91, v27
	v_fmac_f32_e32 v9, v91, v31
	v_fmac_f32_e32 v6, v91, v35
	v_fmac_f32_e32 v7, v91, v39
	v_fmac_f32_e32 v4, v91, v43
	v_fmac_f32_e32 v5, v91, v47
	s_waitcnt lgkmcnt(0)
	v_fmac_f32_e32 v10, v92, v128
	v_fmac_f32_e32 v11, v92, v132
	v_fmac_f32_e32 v8, v92, v136
	v_fmac_f32_e32 v9, v92, v140
	v_fmac_f32_e32 v6, v92, v144
	v_fmac_f32_e32 v7, v92, v148
	v_fmac_f32_e32 v4, v92, v152
	v_fmac_f32_e32 v5, v92, v156
	v_fmac_f32_e32 v10, v93, v129
	v_fmac_f32_e32 v11, v93, v133
	v_fmac_f32_e32 v8, v93, v137
	v_fmac_f32_e32 v9, v93, v141
	v_fmac_f32_e32 v6, v93, v145
	v_fmac_f32_e32 v7, v93, v149
	v_fmac_f32_e32 v4, v93, v153
	v_fmac_f32_e32 v5, v93, v157
	v_fmac_f32_e32 v10, v94, v130
	v_fmac_f32_e32 v11, v94, v134
	v_fmac_f32_e32 v8, v94, v138
	v_fmac_f32_e32 v9, v94, v142
	v_fmac_f32_e32 v6, v94, v146
	v_fmac_f32_e32 v7, v94, v150
	v_fmac_f32_e32 v4, v94, v154
	v_fmac_f32_e32 v5, v94, v158
	v_fmac_f32_e32 v10, v95, v131
	v_fmac_f32_e32 v11, v95, v135
	v_fmac_f32_e32 v8, v95, v139
	v_fmac_f32_e32 v9, v95, v143
	v_fmac_f32_e32 v6, v95, v147
	v_fmac_f32_e32 v7, v95, v151
	v_fmac_f32_e32 v4, v95, v155
	v_fmac_f32_e32 v5, v95, v159
	s_cmp_eq_u32 s17, 1
	s_cbranch_scc1 .Lsw_s2l
	global_load_dword v64, v[2:3], off
	v_lshl_add_u64 v[2:3], v[2:3], 0, s[28:29]
	global_load_dword v65, v[2:3], off
	v_lshl_add_u64 v[2:3], v[2:3], 0, s[28:29]
	global_load_dword v66, v[2:3], off
	v_lshl_add_u64 v[2:3], v[2:3], 0, s[28:29]
	global_load_dword v67, v[2:3], off
	v_lshl_add_u64 v[2:3], v[2:3], 0, s[28:29]
	global_load_dword v68, v[2:3], off
	v_lshl_add_u64 v[2:3], v[2:3], 0, s[28:29]
	global_load_dword v69, v[2:3], off
	v_lshl_add_u64 v[2:3], v[2:3], 0, s[28:29]
	global_load_dword v70, v[2:3], off
	v_lshl_add_u64 v[2:3], v[2:3], 0, s[28:29]
	global_load_dword v71, v[2:3], off
	v_lshl_add_u64 v[2:3], v[2:3], 0, s[28:29]
	global_load_dword v72, v[2:3], off
	v_lshl_add_u64 v[2:3], v[2:3], 0, s[28:29]
	global_load_dword v73, v[2:3], off
	v_lshl_add_u64 v[2:3], v[2:3], 0, s[28:29]
	global_load_dword v74, v[2:3], off
	v_lshl_add_u64 v[2:3], v[2:3], 0, s[28:29]
	global_load_dword v75, v[2:3], off
	v_lshl_add_u64 v[2:3], v[2:3], 0, s[28:29]
	global_load_dword v76, v[2:3], off
	v_lshl_add_u64 v[2:3], v[2:3], 0, s[28:29]
	global_load_dword v77, v[2:3], off
	v_lshl_add_u64 v[2:3], v[2:3], 0, s[28:29]
	global_load_dword v78, v[2:3], off
	v_lshl_add_u64 v[2:3], v[2:3], 0, s[28:29]
	global_load_dword v79, v[2:3], off
	v_lshl_add_u64 v[2:3], v[2:3], 0, s[28:29]
	s_waitcnt vmcnt(32)
	s_branch .Lsw_s2c

; __device__ __forceinline__ void prep_sw_job(const Params& p, int job, float* sm) {
;     ...
;   const float* wp = W + (size_t)(kq * 256) * ldw + col0 + col;
;   const float* scp = sc + kq * 256;
; #pragma unroll 8
;   for (int k = 0; k < 256; ++k) {
;     float w = wp[(size_t)k * ldw];
; #pragma unroll
;     for (int q = 0; q < 8; ++q) acc[q] += scp[q * 1024 + k] * w;
;   }
.Lsw_s2c:
	ds_read_b128 v[16:19], v54 offset:128
	ds_read_b128 v[20:23], v54 offset:4224
	ds_read_b128 v[24:27], v54 offset:8320
	ds_read_b128 v[28:31], v54 offset:12416
	ds_read_b128 v[32:35], v54 offset:16512
	ds_read_b128 v[36:39], v54 offset:20608
	ds_read_b128 v[40:43], v54 offset:24704
	ds_read_b128 v[44:47], v54 offset:28800
	s_waitcnt lgkmcnt(4)
	ds_read_b128 v[128:131], v54 offset:144
	ds_read_b128 v[132:135], v54 offset:4240
	ds_read_b128 v[136:139], v54 offset:8336
	ds_read_b128 v[140:143], v54 offset:12432
	ds_read_b128 v[144:147], v54 offset:16528
	ds_read_b128 v[148:151], v54 offset:20624
	ds_read_b128 v[152:155], v54 offset:24720
	ds_read_b128 v[156:159], v54 offset:28816
	s_waitcnt lgkmcnt(8)
	v_fmac_f32_e32 v10, v96, v16
	v_fmac_f32_e32 v11, v96, v20
	v_fmac_f32_e32 v8, v96, v24
	v_fmac_f32_e32 v9, v96, v28
	v_fmac_f32_e32 v6, v96, v32
	v_fmac_f32_e32 v7, v96, v36
	v_fmac_f32_e32 v4, v96, v40
	v_fmac_f32_e32 v5, v96, v44
	v_fmac_f32_e32 v10, v97, v17
	v_fmac_f32_e32 v11, v97, v21
	v_fmac_f32_e32 v8, v97, v25
	v_fmac_f32_e32 v9, v97, v29
	v_fmac_f32_e32 v6, v97, v33
	v_fmac_f32_e32 v7, v97, v37
	v_fmac_f32_e32 v4, v97, v41
	v_fmac_f32_e32 v5, v97, v45
	v_fmac_f32_e32 v10, v98, v18
	v_fmac_f32_e32 v11, v98, v22
	v_fmac_f32_e32 v8, v98, v26
	v_fmac_f32_e32 v9, v98, v30
	v_fmac_f32_e32 v6, v98, v34
	v_fmac_f32_e32 v7, v98, v38
	v_fmac_f32_e32 v4, v98, v42
	v_fmac_f32_e32 v5, v98, v46
	v_fmac_f32_e32 v10, v99, v19
	v_fmac_f32_e32 v11, v99, v23
	v_fmac_f32_e32 v8, v99, v27
	v_fmac_f32_e32 v9, v99, v31
	v_fmac_f32_e32 v6, v99, v35
	v_fmac_f32_e32 v7, v99, v39
	v_fmac_f32_e32 v4, v99, v43
	v_fmac_f32_e32 v5, v99, v47
	s_waitcnt lgkmcnt(4)
	ds_read_b128 v[16:19], v54 offset:160
	ds_read_b128 v[20:23], v54 offset:4256
	ds_read_b128 v[24:27], v54 offset:8352
	ds_read_b128 v[28:31], v54 offset:12448
	ds_read_b128 v[32:35], v54 offset:16544
	ds_read_b128 v[36:39], v54 offset:20640
	ds_read_b128 v[40:43], v54 offset:24736
	ds_read_b128 v[44:47], v54 offset:28832
	s_waitcnt lgkmcnt(8)
	v_fmac_f32_e32 v10, v100, v128
	v_fmac_f32_e32 v11, v100, v132
	v_fmac_f32_e32 v8, v100, v136
	v_fmac_f32_e32 v9, v100, v140
	v_fmac_f32_e32 v6, v100, v144
	v_fmac_f32_e32 v7, v100, v148
	v_fmac_f32_e32 v4, v100, v152
	v_fmac_f32_e32 v5, v100, v156
	v_fmac_f32_e32 v10, v101, v129
	v_fmac_f32_e32 v11, v101, v133
	v_fmac_f32_e32 v8, v101, v137
	v_fmac_f32_e32 v9, v101, v141
	v_fmac_f32_e32 v6, v101, v145
	v_fmac_f32_e32 v7, v101, v149
	v_fmac_f32_e32 v4, v101, v153
	v_fmac_f32_e32 v5, v101, v157
	v_fmac_f32_e32 v10, v102, v130
	v_fmac_f32_e32 v11, v102, v134
	v_fmac_f32_e32 v8, v102, v138
	v_fmac_f32_e32 v9, v102, v142
	v_fmac_f32_e32 v6, v102, v146
	v_fmac_f32_e32 v7, v102, v150
	v_fmac_f32_e32 v4, v102, v154
	v_fmac_f32_e32 v5, v102, v158
	v_fmac_f32_e32 v10, v103, v131
	v_fmac_f32_e32 v11, v103, v135
	v_fmac_f32_e32 v8, v103, v139
	v_fmac_f32_e32 v9, v103, v143
	v_fmac_f32_e32 v6, v103, v147
	v_fmac_f32_e32 v7, v103, v151
	v_fmac_f32_e32 v4, v103, v155
	v_fmac_f32_e32 v5, v103, v159
	s_waitcnt lgkmcnt(4)
	ds_read_b128 v[128:131], v54 offset:176
	ds_read_b128 v[132:135], v54 offset:4272
	ds_read_b128 v[136:139], v54 offset:8368
	ds_read_b128 v[140:143], v54 offset:12464
	ds_read_b128 v[144:147], v54 offset:16560
	ds_read_b128 v[148:151], v54 offset:20656
	ds_read_b128 v[152:155], v54 offset:24752
	ds_read_b128 v[156:159], v54 offset:28848
	s_waitcnt lgkmcnt(8)
	v_fmac_f32_e32 v10, v104, v16
	v_fmac_f32_e32 v11, v104, v20
	v_fmac_f32_e32 v8, v104, v24
	v_fmac_f32_e32 v9, v104, v28
	v_fmac_f32_e32 v6, v104, v32
	v_fmac_f32_e32 v7, v104, v36
	v_fmac_f32_e32 v4, v104, v40
	v_fmac_f32_e32 v5, v104, v44
	v_fmac_f32_e32 v10, v105, v17
	v_fmac_f32_e32 v11, v105, v21
	v_fmac_f32_e32 v8, v105, v25
	v_fmac_f32_e32 v9, v105, v29
	v_fmac_f32_e32 v6, v105, v33
	v_fmac_f32_e32 v7, v105, v37
	v_fmac_f32_e32 v4, v105, v41
	v_fmac_f32_e32 v5, v105, v45
	v_fmac_f32_e32 v10, v106, v18
	v_fmac_f32_e32 v11, v106, v22
	v_fmac_f32_e32 v8, v106, v26
	v_fmac_f32_e32 v9, v106, v30
	v_fmac_f32_e32 v6, v106, v34
	v_fmac_f32_e32 v7, v106, v38
	v_fmac_f32_e32 v4, v106, v42
	v_fmac_f32_e32 v5, v106, v46
	v_fmac_f32_e32 v10, v107, v19
	v_fmac_f32_e32 v11, v107, v23
	v_fmac_f32_e32 v8, v107, v27
	v_fmac_f32_e32 v9, v107, v31
	v_fmac_f32_e32 v6, v107, v35
	v_fmac_f32_e32 v7, v107, v39
	v_fmac_f32_e32 v4, v107, v43
	v_fmac_f32_e32 v5, v107, v47
	s_waitcnt lgkmcnt(0)
	v_fmac_f32_e32 v10, v108, v128
	v_fmac_f32_e32 v11, v108, v132
	v_fmac_f32_e32 v8, v108, v136
	v_fmac_f32_e32 v9, v108, v140
	v_fmac_f32_e32 v6, v108, v144
	v_fmac_f32_e32 v7, v108, v148
	v_fmac_f32_e32 v4, v108, v152
	v_fmac_f32_e32 v5, v108, v156
	v_fmac_f32_e32 v10, v109, v129
	v_fmac_f32_e32 v11, v109, v133
	v_fmac_f32_e32 v8, v109, v137
	v_fmac_f32_e32 v9, v109, v141
	v_fmac_f32_e32 v6, v109, v145
	v_fmac_f32_e32 v7, v109, v149
	v_fmac_f32_e32 v4, v109, v153
	v_fmac_f32_e32 v5, v109, v157
	v_fmac_f32_e32 v10, v110, v130
	v_fmac_f32_e32 v11, v110, v134
	v_fmac_f32_e32 v8, v110, v138
	v_fmac_f32_e32 v9, v110, v142
	v_fmac_f32_e32 v6, v110, v146
	v_fmac_f32_e32 v7, v110, v150
	v_fmac_f32_e32 v4, v110, v154
	v_fmac_f32_e32 v5, v110, v158
	v_fmac_f32_e32 v10, v111, v131
	v_fmac_f32_e32 v11, v111, v135
	v_fmac_f32_e32 v8, v111, v139
	v_fmac_f32_e32 v9, v111, v143
	v_fmac_f32_e32 v6, v111, v147
	v_fmac_f32_e32 v7, v111, v151
	v_fmac_f32_e32 v4, v111, v155
	v_fmac_f32_e32 v5, v111, v159
	s_cmp_eq_u32 s17, 1
	s_cbranch_scc1 .Lsw_s3l
	global_load_dword v80, v[2:3], off
	v_lshl_add_u64 v[2:3], v[2:3], 0, s[28:29]
	global_load_dword v81, v[2:3], off
	v_lshl_add_u64 v[2:3], v[2:3], 0, s[28:29]
	global_load_dword v82, v[2:3], off
	v_lshl_add_u64 v[2:3], v[2:3], 0, s[28:29]
	global_load_dword v83, v[2:3], off
	v_lshl_add_u64 v[2:3], v[2:3], 0, s[28:29]
	global_load_dword v84, v[2:3], off
	v_lshl_add_u64 v[2:3], v[2:3], 0, s[28:29]
	global_load_dword v85, v[2:3], off
	v_lshl_add_u64 v[2:3], v[2:3], 0, s[28:29]
	global_load_dword v86, v[2:3], off
	v_lshl_add_u64 v[2:3], v[2:3], 0, s[28:29]
	global_load_dword v87, v[2:3], off
	v_lshl_add_u64 v[2:3], v[2:3], 0, s[28:29]
	global_load_dword v88, v[2:3], off
	v_lshl_add_u64 v[2:3], v[2:3], 0, s[28:29]
	global_load_dword v89, v[2:3], off
	v_lshl_add_u64 v[2:3], v[2:3], 0, s[28:29]
	global_load_dword v90, v[2:3], off
	v_lshl_add_u64 v[2:3], v[2:3], 0, s[28:29]
	global_load_dword v91, v[2:3], off
	v_lshl_add_u64 v[2:3], v[2:3], 0, s[28:29]
	global_load_dword v92, v[2:3], off
	v_lshl_add_u64 v[2:3], v[2:3], 0, s[28:29]
	global_load_dword v93, v[2:3], off
	v_lshl_add_u64 v[2:3], v[2:3], 0, s[28:29]
	global_load_dword v94, v[2:3], off
	v_lshl_add_u64 v[2:3], v[2:3], 0, s[28:29]
	global_load_dword v95, v[2:3], off
	v_lshl_add_u64 v[2:3], v[2:3], 0, s[28:29]
	s_waitcnt vmcnt(32)
	s_branch .Lsw_s3c

; __device__ __forceinline__ void prep_sw_job(const Params& p, int job, float* sm) {
;     ...
;   const float* wp = W + (size_t)(kq * 256) * ldw + col0 + col;
;   const float* scp = sc + kq * 256;
; #pragma unroll 8
;   for (int k = 0; k < 256; ++k) {
;     float w = wp[(size_t)k * ldw];
; #pragma unroll
;     for (int q = 0; q < 8; ++q) acc[q] += scp[q * 1024 + k] * w;
;   }
.Lsw_s3c:
	ds_read_b128 v[16:19], v54 offset:192
	ds_read_b128 v[20:23], v54 offset:4288
	ds_read_b128 v[24:27], v54 offset:8384
	ds_read_b128 v[28:31], v54 offset:12480
	ds_read_b128 v[32:35], v54 offset:16576
	ds_read_b128 v[36:39], v54 offset:20672
	ds_read_b128 v[40:43], v54 offset:24768
	ds_read_b128 v[44:47], v54 offset:28864
	s_waitcnt lgkmcnt(4)
	ds_read_b128 v[128:131], v54 offset:208
	ds_read_b128 v[132:135], v54 offset:4304
	ds_read_b128 v[136:139], v54 offset:8400
	ds_read_b128 v[140:143], v54 offset:12496
	ds_read_b128 v[144:147], v54 offset:16592
	ds_read_b128 v[148:151], v54 offset:20688
	ds_read_b128 v[152:155], v54 offset:24784
	ds_read_b128 v[156:159], v54 offset:28880
	s_waitcnt lgkmcnt(8)
	v_fmac_f32_e32 v10, v112, v16
	v_fmac_f32_e32 v11, v112, v20
	v_fmac_f32_e32 v8, v112, v24
	v_fmac_f32_e32 v9, v112, v28
	v_fmac_f32_e32 v6, v112, v32
	v_fmac_f32_e32 v7, v112, v36
	v_fmac_f32_e32 v4, v112, v40
	v_fmac_f32_e32 v5, v112, v44
	v_fmac_f32_e32 v10, v113, v17
	v_fmac_f32_e32 v11, v113, v21
	v_fmac_f32_e32 v8, v113, v25
	v_fmac_f32_e32 v9, v113, v29
	v_fmac_f32_e32 v6, v113, v33
	v_fmac_f32_e32 v7, v113, v37
	v_fmac_f32_e32 v4, v113, v41
	v_fmac_f32_e32 v5, v113, v45
	v_fmac_f32_e32 v10, v114, v18
	v_fmac_f32_e32 v11, v114, v22
	v_fmac_f32_e32 v8, v114, v26
	v_fmac_f32_e32 v9, v114, v30
	v_fmac_f32_e32 v6, v114, v34
	v_fmac_f32_e32 v7, v114, v38
	v_fmac_f32_e32 v4, v114, v42
	v_fmac_f32_e32 v5, v114, v46
	v_fmac_f32_e32 v10, v115, v19
	v_fmac_f32_e32 v11, v115, v23
	v_fmac_f32_e32 v8, v115, v27
	v_fmac_f32_e32 v9, v115, v31
	v_fmac_f32_e32 v6, v115, v35
	v_fmac_f32_e32 v7, v115, v39
	v_fmac_f32_e32 v4, v115, v43
	v_fmac_f32_e32 v5, v115, v47
	s_waitcnt lgkmcnt(4)
	ds_read_b128 v[16:19], v54 offset:224
	ds_read_b128 v[20:23], v54 offset:4320
	ds_read_b128 v[24:27], v54 offset:8416
	ds_read_b128 v[28:31], v54 offset:12512
	ds_read_b128 v[32:35], v54 offset:16608
	ds_read_b128 v[36:39], v54 offset:20704
	ds_read_b128 v[40:43], v54 offset:24800
	ds_read_b128 v[44:47], v54 offset:28896
	s_waitcnt lgkmcnt(8)
	v_fmac_f32_e32 v10, v116, v128
	v_fmac_f32_e32 v11, v116, v132
	v_fmac_f32_e32 v8, v116, v136
	v_fmac_f32_e32 v9, v116, v140
	v_fmac_f32_e32 v6, v116, v144
	v_fmac_f32_e32 v7, v116, v148
	v_fmac_f32_e32 v4, v116, v152
	v_fmac_f32_e32 v5, v116, v156
	v_fmac_f32_e32 v10, v117, v129
	v_fmac_f32_e32 v11, v117, v133
	v_fmac_f32_e32 v8, v117, v137
	v_fmac_f32_e32 v9, v117, v141
	v_fmac_f32_e32 v6, v117, v145
	v_fmac_f32_e32 v7, v117, v149
	v_fmac_f32_e32 v4, v117, v153
	v_fmac_f32_e32 v5, v117, v157
	v_fmac_f32_e32 v10, v118, v130
	v_fmac_f32_e32 v11, v118, v134
	v_fmac_f32_e32 v8, v118, v138
	v_fmac_f32_e32 v9, v118, v142
	v_fmac_f32_e32 v6, v118, v146
	v_fmac_f32_e32 v7, v118, v150
	v_fmac_f32_e32 v4, v118, v154
	v_fmac_f32_e32 v5, v118, v158
	v_fmac_f32_e32 v10, v119, v131
	v_fmac_f32_e32 v11, v119, v135
	v_fmac_f32_e32 v8, v119, v139
	v_fmac_f32_e32 v9, v119, v143
	v_fmac_f32_e32 v6, v119, v147
	v_fmac_f32_e32 v7, v119, v151
	v_fmac_f32_e32 v4, v119, v155
	v_fmac_f32_e32 v5, v119, v159
	s_waitcnt lgkmcnt(4)
	ds_read_b128 v[128:131], v54 offset:240
	ds_read_b128 v[132:135], v54 offset:4336
	ds_read_b128 v[136:139], v54 offset:8432
	ds_read_b128 v[140:143], v54 offset:12528
	ds_read_b128 v[144:147], v54 offset:16624
	ds_read_b128 v[148:151], v54 offset:20720
	ds_read_b128 v[152:155], v54 offset:24816
	ds_read_b128 v[156:159], v54 offset:28912
	s_waitcnt lgkmcnt(8)
	v_fmac_f32_e32 v10, v120, v16
	v_fmac_f32_e32 v11, v120, v20
	v_fmac_f32_e32 v8, v120, v24
	v_fmac_f32_e32 v9, v120, v28
	v_fmac_f32_e32 v6, v120, v32
	v_fmac_f32_e32 v7, v120, v36
	v_fmac_f32_e32 v4, v120, v40
	v_fmac_f32_e32 v5, v120, v44
	v_fmac_f32_e32 v10, v121, v17
	v_fmac_f32_e32 v11, v121, v21
	v_fmac_f32_e32 v8, v121, v25
	v_fmac_f32_e32 v9, v121, v29
	v_fmac_f32_e32 v6, v121, v33
	v_fmac_f32_e32 v7, v121, v37
	v_fmac_f32_e32 v4, v121, v41
	v_fmac_f32_e32 v5, v121, v45
	v_fmac_f32_e32 v10, v122, v18
	v_fmac_f32_e32 v11, v122, v22
	v_fmac_f32_e32 v8, v122, v26
	v_fmac_f32_e32 v9, v122, v30
	v_fmac_f32_e32 v6, v122, v34
	v_fmac_f32_e32 v7, v122, v38
	v_fmac_f32_e32 v4, v122, v42
	v_fmac_f32_e32 v5, v122, v46
	v_fmac_f32_e32 v10, v123, v19
	v_fmac_f32_e32 v11, v123, v23
	v_fmac_f32_e32 v8, v123, v27
	v_fmac_f32_e32 v9, v123, v31
	v_fmac_f32_e32 v6, v123, v35
	v_fmac_f32_e32 v7, v123, v39
	v_fmac_f32_e32 v4, v123, v43
	v_fmac_f32_e32 v5, v123, v47
	s_waitcnt lgkmcnt(0)
	v_fmac_f32_e32 v10, v124, v128
	v_fmac_f32_e32 v11, v124, v132
	v_fmac_f32_e32 v8, v124, v136
	v_fmac_f32_e32 v9, v124, v140
	v_fmac_f32_e32 v6, v124, v144
	v_fmac_f32_e32 v7, v124, v148
	v_fmac_f32_e32 v4, v124, v152
	v_fmac_f32_e32 v5, v124, v156
	v_fmac_f32_e32 v10, v125, v129
	v_fmac_f32_e32 v11, v125, v133
	v_fmac_f32_e32 v8, v125, v137
	v_fmac_f32_e32 v9, v125, v141
	v_fmac_f32_e32 v6, v125, v145
	v_fmac_f32_e32 v7, v125, v149
	v_fmac_f32_e32 v4, v125, v153
	v_fmac_f32_e32 v5, v125, v157
	v_fmac_f32_e32 v10, v126, v130
	v_fmac_f32_e32 v11, v126, v134
	v_fmac_f32_e32 v8, v126, v138
	v_fmac_f32_e32 v9, v126, v142
	v_fmac_f32_e32 v6, v126, v146
	v_fmac_f32_e32 v7, v126, v150
	v_fmac_f32_e32 v4, v126, v154
	v_fmac_f32_e32 v5, v126, v158
	v_fmac_f32_e32 v10, v127, v131
	v_fmac_f32_e32 v11, v127, v135
	v_fmac_f32_e32 v8, v127, v139
	v_fmac_f32_e32 v9, v127, v143
	v_fmac_f32_e32 v6, v127, v147
	v_fmac_f32_e32 v7, v127, v151
	v_fmac_f32_e32 v4, v127, v155
	v_fmac_f32_e32 v5, v127, v159
	s_cmp_eq_u32 s17, 1
	s_cbranch_scc1 .Lsw_done
	global_load_dword v96, v[2:3], off
	v_lshl_add_u64 v[2:3], v[2:3], 0, s[28:29]
	global_load_dword v97, v[2:3], off
	v_lshl_add_u64 v[2:3], v[2:3], 0, s[28:29]
	global_load_dword v98, v[2:3], off
	v_lshl_add_u64 v[2:3], v[2:3], 0, s[28:29]
	global_load_dword v99, v[2:3], off
	v_lshl_add_u64 v[2:3], v[2:3], 0, s[28:29]
	global_load_dword v100, v[2:3], off
	v_lshl_add_u64 v[2:3], v[2:3], 0, s[28:29]
	global_load_dword v101, v[2:3], off
	v_lshl_add_u64 v[2:3], v[2:3], 0, s[28:29]
	global_load_dword v102, v[2:3], off
	v_lshl_add_u64 v[2:3], v[2:3], 0, s[28:29]
	global_load_dword v103, v[2:3], off
	v_lshl_add_u64 v[2:3], v[2:3], 0, s[28:29]
	global_load_dword v104, v[2:3], off
	v_lshl_add_u64 v[2:3], v[2:3], 0, s[28:29]
	global_load_dword v105, v[2:3], off
	v_lshl_add_u64 v[2:3], v[2:3], 0, s[28:29]
	global_load_dword v106, v[2:3], off
	v_lshl_add_u64 v[2:3], v[2:3], 0, s[28:29]
	global_load_dword v107, v[2:3], off
	v_lshl_add_u64 v[2:3], v[2:3], 0, s[28:29]
	global_load_dword v108, v[2:3], off
	v_lshl_add_u64 v[2:3], v[2:3], 0, s[28:29]
	global_load_dword v109, v[2:3], off
	v_lshl_add_u64 v[2:3], v[2:3], 0, s[28:29]
	global_load_dword v110, v[2:3], off
	v_lshl_add_u64 v[2:3], v[2:3], 0, s[28:29]
	global_load_dword v111, v[2:3], off
	v_lshl_add_u64 v[2:3], v[2:3], 0, s[28:29]
	v_add_u32_e32 v54, 0x100, v54
	s_add_i32 s17, s17, -1
	s_branch .Lsw_loop
; __device__ __forceinline__ void prep_sw_job(const Params& p, int job, float* sm) {
;     ...
; #pragma unroll
;   for (int q = 0; q < 8; ++q) red[(kq * 8 + q) * 64 + col] = acc[q];
;   __syncthreads();
; #pragma unroll
;   for (int i = 0; i < 2; ++i) {
;     int o = tid + i * 256;
;     int sq = o >> 6, c = o & 63;
;     float v = red[(0 * 8 + sq) * 64 + c] + red[(1 * 8 + sq) * 64 + c] + red[(2 * 8 + sq) * 64 + c] + red[(3 * 8 + sq) * 64 + c];
;     int n = col0 + c;
;     int nn = (t == 0) ? n : ((n >> 4) * 32 + (n & 15) + (up ? 16 : 0));
;     outp[(size_t)(sg * 8 + sq) * ldo + nn] = v;
;   }
;   __syncthreads();
.Lsw_done:
	v_lshlrev_b32_e32 v2, 11, v1
	v_add3_u32 v2, s65, v2, v198
	ds_write2st64_b32 v2, v10, v11 offset0:128 offset1:129
	ds_write2st64_b32 v2, v8, v9 offset0:130 offset1:131
	ds_write2st64_b32 v2, v6, v7 offset0:132 offset1:133
	ds_write2st64_b32 v2, v4, v5 offset0:134 offset1:135
	v_add_u32_e32 v6, s16, v12
	v_lshlrev_b32_e32 v2, 1, v6
	s_and_b64 s[16:17], s[18:19], exec
	v_and_b32_e32 v4, 0x3fffffc0, v0
	v_and_b32_e32 v2, 0xffffffe0, v2
	v_and_b32_e32 v3, 15, v6
	s_cselect_b32 s16, 16, 0
	v_lshlrev_b32_e32 v4, 2, v4
	v_or3_b32 v7, v3, s16, v2
	v_lshl_add_u32 v2, v0, 2, s65
	v_add3_u32 v8, s65, v4, v198
	s_waitcnt lgkmcnt(0)
	s_barrier
	ds_read2st64_b32 v[2:3], v2 offset0:128 offset1:132
	ds_read2st64_b32 v[4:5], v8 offset0:136 offset1:144
	s_lshl_b32 s16, s27, 3
	v_cndmask_b32_e64 v6, v7, v6, s[8:9]
	v_ashrrev_i32_e32 v7, 31, v6
	v_lshl_add_u64 v[6:7], v[6:7], 2, s[24:25]
	s_waitcnt lgkmcnt(0)
	v_add_f32_e32 v2, v2, v4
	ds_read_b32 v4, v8 offset:38912
	v_add_u32_e32 v8, 0x100, v0
	v_and_b32_e32 v0, 0x3fffffc0, v8
	v_lshlrev_b32_e32 v0, 2, v0
	v_add_f32_e32 v2, v2, v5
	v_add3_u32 v0, s65, v0, v198
	ds_read_b32 v9, v0 offset:38912
	s_waitcnt lgkmcnt(1)
	v_add_f32_e32 v2, v2, v4
	v_add_u32_e32 v4, s16, v1
	ds_read2st64_b32 v[0:1], v0 offset0:136 offset1:144
	v_mad_i64_i32 v[4:5], s[8:9], s26, v4, 0
	v_lshl_add_u64 v[4:5], v[4:5], 2, v[6:7]
	global_store_dword v[4:5], v2, off
	s_waitcnt lgkmcnt(0)
	v_add_f32_e32 v0, v3, v0
	v_ashrrev_i32_e32 v2, 6, v8
	v_add_f32_e32 v0, v0, v1
	v_add_f32_e32 v3, v0, v9
	v_add_u32_e32 v0, s16, v2
	v_mad_i64_i32 v[0:1], s[8:9], s26, v0, 0
	s_add_i32 s46, s46, s96
	v_lshl_add_u64 v[0:1], v[0:1], 2, v[6:7]
	s_cmpk_gt_i32 s46, 0x685
	global_store_dword v[0:1], v3, off
	s_barrier
	s_cbranch_scc0 .LBB0_733
